# expert dot products via exact fp8->bf16 conversion and v_dot2 (bf16 x bf16 products are exact, f32 accumulation); x kept as stored bf16 pairs
# baseline (speedup 1.0000x reference)
.Lex_half:
	s_lshl_b32 s10, s12, 2
	v_add_u32_e32 v64, s10, v79
	v_ashrrev_i32_e32 v65, 31, v64
	v_lshl_add_u64 v[64:65], s[28:29], 0, v[64:65]
	v_lshlrev_b64 v[0:1], 11, v[64:65]
	v_lshl_add_u64 v[0:1], v[80:81], 0, v[0:1]
	global_load_dwordx4 v[216:219], v[0:1], off
	global_load_dwordx4 v[220:223], v[0:1], off offset:16
	s_lshl_b32 s10, s12, 2
	s_add_i32 s10, s10, 1
	v_add_u32_e32 v64, s10, v79
	v_ashrrev_i32_e32 v65, 31, v64
	v_lshl_add_u64 v[64:65], s[28:29], 0, v[64:65]
	v_lshlrev_b64 v[0:1], 11, v[64:65]
	v_lshl_add_u64 v[0:1], v[80:81], 0, v[0:1]
	global_load_dwordx4 v[224:227], v[0:1], off
	global_load_dwordx4 v[228:231], v[0:1], off offset:16
	s_lshl_b32 s10, s12, 2
	s_add_i32 s10, s10, 2
	v_add_u32_e32 v64, s10, v79
	v_ashrrev_i32_e32 v65, 31, v64
	v_lshl_add_u64 v[64:65], s[28:29], 0, v[64:65]
	v_lshlrev_b64 v[0:1], 11, v[64:65]
	v_lshl_add_u64 v[0:1], v[80:81], 0, v[0:1]
	global_load_dwordx4 v[232:235], v[0:1], off
	global_load_dwordx4 v[236:239], v[0:1], off offset:16
	s_lshl_b32 s10, s12, 2
	s_add_i32 s10, s10, 3
	v_add_u32_e32 v64, s10, v79
	v_ashrrev_i32_e32 v65, 31, v64
	v_lshl_add_u64 v[64:65], s[28:29], 0, v[64:65]
	v_lshlrev_b64 v[0:1], 11, v[64:65]
	v_lshl_add_u64 v[0:1], v[80:81], 0, v[0:1]
	global_load_dwordx4 v[240:243], v[0:1], off
	global_load_dwordx4 v[244:247], v[0:1], off offset:16
	s_lshl_b32 s10, s12, 2
	v_add_u32_e32 v255, s10, v79
	v_lshlrev_b32_e32 v255, 11, v255
	v_and_b32_e32 v20, 63, v214
	v_lshl_add_u32 v22, v20, 4, v255
	ds_read_b32 v4, v22 offset:0
	ds_read_b32 v5, v22 offset:1024
	ds_read_b32 v6, v22 offset:2048
	ds_read_b32 v7, v22 offset:3072
	ds_read_b32 v8, v22 offset:4096
	ds_read_b32 v9, v22 offset:5120
	ds_read_b32 v10, v22 offset:6144
	ds_read_b32 v11, v22 offset:7168
	v_or_b32_e32 v23, 64, v20
	s_waitcnt lgkmcnt(0)
	v_lshl_or_b32 v4, v4, 7, v20
	v_lshl_or_b32 v5, v5, 7, v23
	v_lshl_or_b32 v6, v6, 7, v20
	v_lshl_or_b32 v7, v7, 7, v23
	v_lshl_or_b32 v8, v8, 7, v20
	v_lshl_or_b32 v9, v9, 7, v23
	v_lshl_or_b32 v10, v10, 7, v20
	v_lshl_or_b32 v11, v11, 7, v23
	v_xor_b32_e32 v21, 1, v20
	v_lshlrev_b32_e32 v21, 2, v21
	ds_bpermute_b32 v12, v21, v4
	ds_bpermute_b32 v13, v21, v5
	ds_bpermute_b32 v14, v21, v6
	ds_bpermute_b32 v15, v21, v7
	ds_bpermute_b32 v16, v21, v8
	ds_bpermute_b32 v17, v21, v9
	ds_bpermute_b32 v18, v21, v10
	ds_bpermute_b32 v19, v21, v11
	v_bfe_u32 v22, v20, 0, 1
	v_bfe_u32 v23, v20, 1, 1
	v_xor_b32_e32 v22, v22, v23
	v_cmp_eq_u32_e32 vcc, 0, v22
	s_waitcnt lgkmcnt(6)
	v_min_u32_e32 v22, v4, v12
	v_max_u32_e32 v23, v4, v12
	v_min_u32_e32 v24, v5, v13
	v_max_u32_e32 v25, v5, v13
	v_cndmask_b32_e32 v4, v23, v22, vcc
	v_cndmask_b32_e32 v5, v25, v24, vcc
	s_waitcnt lgkmcnt(4)
	v_min_u32_e32 v22, v6, v14
	v_max_u32_e32 v23, v6, v14
	v_min_u32_e32 v24, v7, v15
	v_max_u32_e32 v25, v7, v15
	v_cndmask_b32_e32 v6, v23, v22, vcc
	v_cndmask_b32_e32 v7, v25, v24, vcc
	s_waitcnt lgkmcnt(2)
	v_min_u32_e32 v22, v8, v16
	v_max_u32_e32 v23, v8, v16
	v_min_u32_e32 v24, v9, v17
	v_max_u32_e32 v25, v9, v17
	v_cndmask_b32_e32 v8, v23, v22, vcc
	v_cndmask_b32_e32 v9, v25, v24, vcc
	s_waitcnt lgkmcnt(0)
	v_min_u32_e32 v22, v10, v18
	v_max_u32_e32 v23, v10, v18
	v_min_u32_e32 v24, v11, v19
	v_max_u32_e32 v25, v11, v19
	v_cndmask_b32_e32 v10, v23, v22, vcc
	v_cndmask_b32_e32 v11, v25, v24, vcc
	v_xor_b32_e32 v21, 2, v20
	v_lshlrev_b32_e32 v21, 2, v21
	ds_bpermute_b32 v12, v21, v4
	ds_bpermute_b32 v13, v21, v5
	ds_bpermute_b32 v14, v21, v6
	ds_bpermute_b32 v15, v21, v7
	ds_bpermute_b32 v16, v21, v8
	ds_bpermute_b32 v17, v21, v9
	ds_bpermute_b32 v18, v21, v10
	ds_bpermute_b32 v19, v21, v11
	v_bfe_u32 v22, v20, 1, 1
	v_bfe_u32 v23, v20, 2, 1
	v_xor_b32_e32 v22, v22, v23
	v_cmp_eq_u32_e32 vcc, 0, v22
	s_waitcnt lgkmcnt(6)
	v_min_u32_e32 v22, v4, v12
	v_max_u32_e32 v23, v4, v12
	v_min_u32_e32 v24, v5, v13
	v_max_u32_e32 v25, v5, v13
	v_cndmask_b32_e32 v4, v23, v22, vcc
	v_cndmask_b32_e32 v5, v25, v24, vcc
	s_waitcnt lgkmcnt(4)
	v_min_u32_e32 v22, v6, v14
	v_max_u32_e32 v23, v6, v14
	v_min_u32_e32 v24, v7, v15
	v_max_u32_e32 v25, v7, v15
	v_cndmask_b32_e32 v6, v23, v22, vcc
	v_cndmask_b32_e32 v7, v25, v24, vcc
	s_waitcnt lgkmcnt(2)
	v_min_u32_e32 v22, v8, v16
	v_max_u32_e32 v23, v8, v16
	v_min_u32_e32 v24, v9, v17
	v_max_u32_e32 v25, v9, v17
	v_cndmask_b32_e32 v8, v23, v22, vcc
	v_cndmask_b32_e32 v9, v25, v24, vcc
	s_waitcnt lgkmcnt(0)
	v_min_u32_e32 v22, v10, v18
	v_max_u32_e32 v23, v10, v18
	v_min_u32_e32 v24, v11, v19
	v_max_u32_e32 v25, v11, v19
	v_cndmask_b32_e32 v10, v23, v22, vcc
	v_cndmask_b32_e32 v11, v25, v24, vcc
	v_xor_b32_e32 v21, 1, v20
	v_lshlrev_b32_e32 v21, 2, v21
	ds_bpermute_b32 v12, v21, v4
	ds_bpermute_b32 v13, v21, v5
	ds_bpermute_b32 v14, v21, v6
	ds_bpermute_b32 v15, v21, v7
	ds_bpermute_b32 v16, v21, v8
	ds_bpermute_b32 v17, v21, v9
	ds_bpermute_b32 v18, v21, v10
	ds_bpermute_b32 v19, v21, v11
	v_bfe_u32 v22, v20, 0, 1
	v_bfe_u32 v23, v20, 2, 1
	v_xor_b32_e32 v22, v22, v23
	v_cmp_eq_u32_e32 vcc, 0, v22
	s_waitcnt lgkmcnt(6)
	v_min_u32_e32 v22, v4, v12
	v_max_u32_e32 v23, v4, v12
	v_min_u32_e32 v24, v5, v13
	v_max_u32_e32 v25, v5, v13
	v_cndmask_b32_e32 v4, v23, v22, vcc
	v_cndmask_b32_e32 v5, v25, v24, vcc
	s_waitcnt lgkmcnt(4)
	v_min_u32_e32 v22, v6, v14
	v_max_u32_e32 v23, v6, v14
	v_min_u32_e32 v24, v7, v15
	v_max_u32_e32 v25, v7, v15
	v_cndmask_b32_e32 v6, v23, v22, vcc
	v_cndmask_b32_e32 v7, v25, v24, vcc
	s_waitcnt lgkmcnt(2)
	v_min_u32_e32 v22, v8, v16
	v_max_u32_e32 v23, v8, v16
	v_min_u32_e32 v24, v9, v17
	v_max_u32_e32 v25, v9, v17
	v_cndmask_b32_e32 v8, v23, v22, vcc
	v_cndmask_b32_e32 v9, v25, v24, vcc
	s_waitcnt lgkmcnt(0)
	v_min_u32_e32 v22, v10, v18
	v_max_u32_e32 v23, v10, v18
	v_min_u32_e32 v24, v11, v19
	v_max_u32_e32 v25, v11, v19
	v_cndmask_b32_e32 v10, v23, v22, vcc
	v_cndmask_b32_e32 v11, v25, v24, vcc
	v_xor_b32_e32 v21, 4, v20
	v_lshlrev_b32_e32 v21, 2, v21
	ds_bpermute_b32 v12, v21, v4
	ds_bpermute_b32 v13, v21, v5
	ds_bpermute_b32 v14, v21, v6
	ds_bpermute_b32 v15, v21, v7
	ds_bpermute_b32 v16, v21, v8
	ds_bpermute_b32 v17, v21, v9
	ds_bpermute_b32 v18, v21, v10
	ds_bpermute_b32 v19, v21, v11
	v_bfe_u32 v22, v20, 2, 1
	v_bfe_u32 v23, v20, 3, 1
	v_xor_b32_e32 v22, v22, v23
	v_cmp_eq_u32_e32 vcc, 0, v22
	s_waitcnt lgkmcnt(6)
	v_min_u32_e32 v22, v4, v12
	v_max_u32_e32 v23, v4, v12
	v_min_u32_e32 v24, v5, v13
	v_max_u32_e32 v25, v5, v13
	v_cndmask_b32_e32 v4, v23, v22, vcc
	v_cndmask_b32_e32 v5, v25, v24, vcc
	s_waitcnt lgkmcnt(4)
	v_min_u32_e32 v22, v6, v14
	v_max_u32_e32 v23, v6, v14
	v_min_u32_e32 v24, v7, v15
	v_max_u32_e32 v25, v7, v15
	v_cndmask_b32_e32 v6, v23, v22, vcc
	v_cndmask_b32_e32 v7, v25, v24, vcc
	s_waitcnt lgkmcnt(2)
	v_min_u32_e32 v22, v8, v16
	v_max_u32_e32 v23, v8, v16
	v_min_u32_e32 v24, v9, v17
	v_max_u32_e32 v25, v9, v17
	v_cndmask_b32_e32 v8, v23, v22, vcc
	v_cndmask_b32_e32 v9, v25, v24, vcc
	s_waitcnt lgkmcnt(0)
	v_min_u32_e32 v22, v10, v18
	v_max_u32_e32 v23, v10, v18
	v_min_u32_e32 v24, v11, v19
	v_max_u32_e32 v25, v11, v19
	v_cndmask_b32_e32 v10, v23, v22, vcc
	v_cndmask_b32_e32 v11, v25, v24, vcc
	v_xor_b32_e32 v21, 2, v20
	v_lshlrev_b32_e32 v21, 2, v21
	ds_bpermute_b32 v12, v21, v4
	ds_bpermute_b32 v13, v21, v5
	ds_bpermute_b32 v14, v21, v6
	ds_bpermute_b32 v15, v21, v7
	ds_bpermute_b32 v16, v21, v8
	ds_bpermute_b32 v17, v21, v9
	ds_bpermute_b32 v18, v21, v10
	ds_bpermute_b32 v19, v21, v11
	v_bfe_u32 v22, v20, 1, 1
	v_bfe_u32 v23, v20, 3, 1
	v_xor_b32_e32 v22, v22, v23
	v_cmp_eq_u32_e32 vcc, 0, v22
	s_waitcnt lgkmcnt(6)
	v_min_u32_e32 v22, v4, v12
	v_max_u32_e32 v23, v4, v12
	v_min_u32_e32 v24, v5, v13
	v_max_u32_e32 v25, v5, v13
	v_cndmask_b32_e32 v4, v23, v22, vcc
	v_cndmask_b32_e32 v5, v25, v24, vcc
	s_waitcnt lgkmcnt(4)
	v_min_u32_e32 v22, v6, v14
	v_max_u32_e32 v23, v6, v14
	v_min_u32_e32 v24, v7, v15
	v_max_u32_e32 v25, v7, v15
	v_cndmask_b32_e32 v6, v23, v22, vcc
	v_cndmask_b32_e32 v7, v25, v24, vcc
	s_waitcnt lgkmcnt(2)
	v_min_u32_e32 v22, v8, v16
	v_max_u32_e32 v23, v8, v16
	v_min_u32_e32 v24, v9, v17
	v_max_u32_e32 v25, v9, v17
	v_cndmask_b32_e32 v8, v23, v22, vcc
	v_cndmask_b32_e32 v9, v25, v24, vcc
	s_waitcnt lgkmcnt(0)
	v_min_u32_e32 v22, v10, v18
	v_max_u32_e32 v23, v10, v18
	v_min_u32_e32 v24, v11, v19
	v_max_u32_e32 v25, v11, v19
	v_cndmask_b32_e32 v10, v23, v22, vcc
	v_cndmask_b32_e32 v11, v25, v24, vcc
	v_xor_b32_e32 v21, 1, v20
	v_lshlrev_b32_e32 v21, 2, v21
	ds_bpermute_b32 v12, v21, v4
	ds_bpermute_b32 v13, v21, v5
	ds_bpermute_b32 v14, v21, v6
	ds_bpermute_b32 v15, v21, v7
	ds_bpermute_b32 v16, v21, v8
	ds_bpermute_b32 v17, v21, v9
	ds_bpermute_b32 v18, v21, v10
	ds_bpermute_b32 v19, v21, v11
	v_bfe_u32 v22, v20, 0, 1
	v_bfe_u32 v23, v20, 3, 1
	v_xor_b32_e32 v22, v22, v23
	v_cmp_eq_u32_e32 vcc, 0, v22
	s_waitcnt lgkmcnt(6)
	v_min_u32_e32 v22, v4, v12
	v_max_u32_e32 v23, v4, v12
	v_min_u32_e32 v24, v5, v13
	v_max_u32_e32 v25, v5, v13
	v_cndmask_b32_e32 v4, v23, v22, vcc
	v_cndmask_b32_e32 v5, v25, v24, vcc
	s_waitcnt lgkmcnt(4)
	v_min_u32_e32 v22, v6, v14
	v_max_u32_e32 v23, v6, v14
	v_min_u32_e32 v24, v7, v15
	v_max_u32_e32 v25, v7, v15
	v_cndmask_b32_e32 v6, v23, v22, vcc
	v_cndmask_b32_e32 v7, v25, v24, vcc
	s_waitcnt lgkmcnt(2)
	v_min_u32_e32 v22, v8, v16
	v_max_u32_e32 v23, v8, v16
	v_min_u32_e32 v24, v9, v17
	v_max_u32_e32 v25, v9, v17
	v_cndmask_b32_e32 v8, v23, v22, vcc
	v_cndmask_b32_e32 v9, v25, v24, vcc
	s_waitcnt lgkmcnt(0)
	v_min_u32_e32 v22, v10, v18
	v_max_u32_e32 v23, v10, v18
	v_min_u32_e32 v24, v11, v19
	v_max_u32_e32 v25, v11, v19
	v_cndmask_b32_e32 v10, v23, v22, vcc
	v_cndmask_b32_e32 v11, v25, v24, vcc
	v_xor_b32_e32 v21, 8, v20
	v_lshlrev_b32_e32 v21, 2, v21
	ds_bpermute_b32 v12, v21, v4
	ds_bpermute_b32 v13, v21, v5
	ds_bpermute_b32 v14, v21, v6
	ds_bpermute_b32 v15, v21, v7
	ds_bpermute_b32 v16, v21, v8
	ds_bpermute_b32 v17, v21, v9
	ds_bpermute_b32 v18, v21, v10
	ds_bpermute_b32 v19, v21, v11
	v_bfe_u32 v22, v20, 3, 1
	v_bfe_u32 v23, v20, 4, 1
	v_xor_b32_e32 v22, v22, v23
	v_cmp_eq_u32_e32 vcc, 0, v22
	s_waitcnt lgkmcnt(6)
	v_min_u32_e32 v22, v4, v12
	v_max_u32_e32 v23, v4, v12
	v_min_u32_e32 v24, v5, v13
	v_max_u32_e32 v25, v5, v13
	v_cndmask_b32_e32 v4, v23, v22, vcc
	v_cndmask_b32_e32 v5, v25, v24, vcc
	s_waitcnt lgkmcnt(4)
	v_min_u32_e32 v22, v6, v14
	v_max_u32_e32 v23, v6, v14
	v_min_u32_e32 v24, v7, v15
	v_max_u32_e32 v25, v7, v15
	v_cndmask_b32_e32 v6, v23, v22, vcc
	v_cndmask_b32_e32 v7, v25, v24, vcc
	s_waitcnt lgkmcnt(2)
	v_min_u32_e32 v22, v8, v16
	v_max_u32_e32 v23, v8, v16
	v_min_u32_e32 v24, v9, v17
	v_max_u32_e32 v25, v9, v17
	v_cndmask_b32_e32 v8, v23, v22, vcc
	v_cndmask_b32_e32 v9, v25, v24, vcc
	s_waitcnt lgkmcnt(0)
	v_min_u32_e32 v22, v10, v18
	v_max_u32_e32 v23, v10, v18
	v_min_u32_e32 v24, v11, v19
	v_max_u32_e32 v25, v11, v19
	v_cndmask_b32_e32 v10, v23, v22, vcc
	v_cndmask_b32_e32 v11, v25, v24, vcc
	v_xor_b32_e32 v21, 4, v20
	v_lshlrev_b32_e32 v21, 2, v21
	ds_bpermute_b32 v12, v21, v4
	ds_bpermute_b32 v13, v21, v5
	ds_bpermute_b32 v14, v21, v6
	ds_bpermute_b32 v15, v21, v7
	ds_bpermute_b32 v16, v21, v8
	ds_bpermute_b32 v17, v21, v9
	ds_bpermute_b32 v18, v21, v10
	ds_bpermute_b32 v19, v21, v11
	v_bfe_u32 v22, v20, 2, 1
	v_bfe_u32 v23, v20, 4, 1
	v_xor_b32_e32 v22, v22, v23
	v_cmp_eq_u32_e32 vcc, 0, v22
	s_waitcnt lgkmcnt(6)
	v_min_u32_e32 v22, v4, v12
	v_max_u32_e32 v23, v4, v12
	v_min_u32_e32 v24, v5, v13
	v_max_u32_e32 v25, v5, v13
	v_cndmask_b32_e32 v4, v23, v22, vcc
	v_cndmask_b32_e32 v5, v25, v24, vcc
	s_waitcnt lgkmcnt(4)
	v_min_u32_e32 v22, v6, v14
	v_max_u32_e32 v23, v6, v14
	v_min_u32_e32 v24, v7, v15
	v_max_u32_e32 v25, v7, v15
	v_cndmask_b32_e32 v6, v23, v22, vcc
	v_cndmask_b32_e32 v7, v25, v24, vcc
	s_waitcnt lgkmcnt(2)
	v_min_u32_e32 v22, v8, v16
	v_max_u32_e32 v23, v8, v16
	v_min_u32_e32 v24, v9, v17
	v_max_u32_e32 v25, v9, v17
	v_cndmask_b32_e32 v8, v23, v22, vcc
	v_cndmask_b32_e32 v9, v25, v24, vcc
	s_waitcnt lgkmcnt(0)
	v_min_u32_e32 v22, v10, v18
	v_max_u32_e32 v23, v10, v18
	v_min_u32_e32 v24, v11, v19
	v_max_u32_e32 v25, v11, v19
	v_cndmask_b32_e32 v10, v23, v22, vcc
	v_cndmask_b32_e32 v11, v25, v24, vcc
	v_xor_b32_e32 v21, 2, v20
	v_lshlrev_b32_e32 v21, 2, v21
	ds_bpermute_b32 v12, v21, v4
	ds_bpermute_b32 v13, v21, v5
	ds_bpermute_b32 v14, v21, v6
	ds_bpermute_b32 v15, v21, v7
	ds_bpermute_b32 v16, v21, v8
	ds_bpermute_b32 v17, v21, v9
	ds_bpermute_b32 v18, v21, v10
	ds_bpermute_b32 v19, v21, v11
	v_bfe_u32 v22, v20, 1, 1
	v_bfe_u32 v23, v20, 4, 1
	v_xor_b32_e32 v22, v22, v23
	v_cmp_eq_u32_e32 vcc, 0, v22
	s_waitcnt lgkmcnt(6)
	v_min_u32_e32 v22, v4, v12
	v_max_u32_e32 v23, v4, v12
	v_min_u32_e32 v24, v5, v13
	v_max_u32_e32 v25, v5, v13
	v_cndmask_b32_e32 v4, v23, v22, vcc
	v_cndmask_b32_e32 v5, v25, v24, vcc
	s_waitcnt lgkmcnt(4)
	v_min_u32_e32 v22, v6, v14
	v_max_u32_e32 v23, v6, v14
	v_min_u32_e32 v24, v7, v15
	v_max_u32_e32 v25, v7, v15
	v_cndmask_b32_e32 v6, v23, v22, vcc
	v_cndmask_b32_e32 v7, v25, v24, vcc
	s_waitcnt lgkmcnt(2)
	v_min_u32_e32 v22, v8, v16
	v_max_u32_e32 v23, v8, v16
	v_min_u32_e32 v24, v9, v17
	v_max_u32_e32 v25, v9, v17
	v_cndmask_b32_e32 v8, v23, v22, vcc
	v_cndmask_b32_e32 v9, v25, v24, vcc
	s_waitcnt lgkmcnt(0)
	v_min_u32_e32 v22, v10, v18
	v_max_u32_e32 v23, v10, v18
	v_min_u32_e32 v24, v11, v19
	v_max_u32_e32 v25, v11, v19
	v_cndmask_b32_e32 v10, v23, v22, vcc
	v_cndmask_b32_e32 v11, v25, v24, vcc
	v_xor_b32_e32 v21, 1, v20
	v_lshlrev_b32_e32 v21, 2, v21
	ds_bpermute_b32 v12, v21, v4
	ds_bpermute_b32 v13, v21, v5
	ds_bpermute_b32 v14, v21, v6
	ds_bpermute_b32 v15, v21, v7
	ds_bpermute_b32 v16, v21, v8
	ds_bpermute_b32 v17, v21, v9
	ds_bpermute_b32 v18, v21, v10
	ds_bpermute_b32 v19, v21, v11
	v_bfe_u32 v22, v20, 0, 1
	v_bfe_u32 v23, v20, 4, 1
	v_xor_b32_e32 v22, v22, v23
	v_cmp_eq_u32_e32 vcc, 0, v22
	s_waitcnt lgkmcnt(6)
	v_min_u32_e32 v22, v4, v12
	v_max_u32_e32 v23, v4, v12
	v_min_u32_e32 v24, v5, v13
	v_max_u32_e32 v25, v5, v13
	v_cndmask_b32_e32 v4, v23, v22, vcc
	v_cndmask_b32_e32 v5, v25, v24, vcc
	s_waitcnt lgkmcnt(4)
	v_min_u32_e32 v22, v6, v14
	v_max_u32_e32 v23, v6, v14
	v_min_u32_e32 v24, v7, v15
	v_max_u32_e32 v25, v7, v15
	v_cndmask_b32_e32 v6, v23, v22, vcc
	v_cndmask_b32_e32 v7, v25, v24, vcc
	s_waitcnt lgkmcnt(2)
	v_min_u32_e32 v22, v8, v16
	v_max_u32_e32 v23, v8, v16
	v_min_u32_e32 v24, v9, v17
	v_max_u32_e32 v25, v9, v17
	v_cndmask_b32_e32 v8, v23, v22, vcc
	v_cndmask_b32_e32 v9, v25, v24, vcc
	s_waitcnt lgkmcnt(0)
	v_min_u32_e32 v22, v10, v18
	v_max_u32_e32 v23, v10, v18
	v_min_u32_e32 v24, v11, v19
	v_max_u32_e32 v25, v11, v19
	v_cndmask_b32_e32 v10, v23, v22, vcc
	v_cndmask_b32_e32 v11, v25, v24, vcc
	v_xor_b32_e32 v21, 16, v20
	v_lshlrev_b32_e32 v21, 2, v21
	ds_bpermute_b32 v12, v21, v4
	ds_bpermute_b32 v13, v21, v5
	ds_bpermute_b32 v14, v21, v6
	ds_bpermute_b32 v15, v21, v7
	ds_bpermute_b32 v16, v21, v8
	ds_bpermute_b32 v17, v21, v9
	ds_bpermute_b32 v18, v21, v10
	ds_bpermute_b32 v19, v21, v11
	v_bfe_u32 v22, v20, 4, 1
	v_bfe_u32 v23, v20, 5, 1
	v_xor_b32_e32 v22, v22, v23
	v_cmp_eq_u32_e32 vcc, 0, v22
	s_waitcnt lgkmcnt(6)
	v_min_u32_e32 v22, v4, v12
	v_max_u32_e32 v23, v4, v12
	v_min_u32_e32 v24, v5, v13
	v_max_u32_e32 v25, v5, v13
	v_cndmask_b32_e32 v4, v23, v22, vcc
	v_cndmask_b32_e32 v5, v25, v24, vcc
	s_waitcnt lgkmcnt(4)
	v_min_u32_e32 v22, v6, v14
	v_max_u32_e32 v23, v6, v14
	v_min_u32_e32 v24, v7, v15
	v_max_u32_e32 v25, v7, v15
	v_cndmask_b32_e32 v6, v23, v22, vcc
	v_cndmask_b32_e32 v7, v25, v24, vcc
	s_waitcnt lgkmcnt(2)
	v_min_u32_e32 v22, v8, v16
	v_max_u32_e32 v23, v8, v16
	v_min_u32_e32 v24, v9, v17
	v_max_u32_e32 v25, v9, v17
	v_cndmask_b32_e32 v8, v23, v22, vcc
	v_cndmask_b32_e32 v9, v25, v24, vcc
	s_waitcnt lgkmcnt(0)
	v_min_u32_e32 v22, v10, v18
	v_max_u32_e32 v23, v10, v18
	v_min_u32_e32 v24, v11, v19
	v_max_u32_e32 v25, v11, v19
	v_cndmask_b32_e32 v10, v23, v22, vcc
	v_cndmask_b32_e32 v11, v25, v24, vcc
	v_xor_b32_e32 v21, 8, v20
	v_lshlrev_b32_e32 v21, 2, v21
	ds_bpermute_b32 v12, v21, v4
	ds_bpermute_b32 v13, v21, v5
	ds_bpermute_b32 v14, v21, v6
	ds_bpermute_b32 v15, v21, v7
	ds_bpermute_b32 v16, v21, v8
	ds_bpermute_b32 v17, v21, v9
	ds_bpermute_b32 v18, v21, v10
	ds_bpermute_b32 v19, v21, v11
	v_bfe_u32 v22, v20, 3, 1
	v_bfe_u32 v23, v20, 5, 1
	v_xor_b32_e32 v22, v22, v23
	v_cmp_eq_u32_e32 vcc, 0, v22
	s_waitcnt lgkmcnt(6)
	v_min_u32_e32 v22, v4, v12
	v_max_u32_e32 v23, v4, v12
	v_min_u32_e32 v24, v5, v13
	v_max_u32_e32 v25, v5, v13
	v_cndmask_b32_e32 v4, v23, v22, vcc
	v_cndmask_b32_e32 v5, v25, v24, vcc
	s_waitcnt lgkmcnt(4)
	v_min_u32_e32 v22, v6, v14
	v_max_u32_e32 v23, v6, v14
	v_min_u32_e32 v24, v7, v15
	v_max_u32_e32 v25, v7, v15
	v_cndmask_b32_e32 v6, v23, v22, vcc
	v_cndmask_b32_e32 v7, v25, v24, vcc
	s_waitcnt lgkmcnt(2)
	v_min_u32_e32 v22, v8, v16
	v_max_u32_e32 v23, v8, v16
	v_min_u32_e32 v24, v9, v17
	v_max_u32_e32 v25, v9, v17
	v_cndmask_b32_e32 v8, v23, v22, vcc
	v_cndmask_b32_e32 v9, v25, v24, vcc
	s_waitcnt lgkmcnt(0)
	v_min_u32_e32 v22, v10, v18
	v_max_u32_e32 v23, v10, v18
	v_min_u32_e32 v24, v11, v19
	v_max_u32_e32 v25, v11, v19
	v_cndmask_b32_e32 v10, v23, v22, vcc
	v_cndmask_b32_e32 v11, v25, v24, vcc
	v_xor_b32_e32 v21, 4, v20
	v_lshlrev_b32_e32 v21, 2, v21
	ds_bpermute_b32 v12, v21, v4
	ds_bpermute_b32 v13, v21, v5
	ds_bpermute_b32 v14, v21, v6
	ds_bpermute_b32 v15, v21, v7
	ds_bpermute_b32 v16, v21, v8
	ds_bpermute_b32 v17, v21, v9
	ds_bpermute_b32 v18, v21, v10
	ds_bpermute_b32 v19, v21, v11
	v_bfe_u32 v22, v20, 2, 1
	v_bfe_u32 v23, v20, 5, 1
	v_xor_b32_e32 v22, v22, v23
	v_cmp_eq_u32_e32 vcc, 0, v22
	s_waitcnt lgkmcnt(6)
	v_min_u32_e32 v22, v4, v12
	v_max_u32_e32 v23, v4, v12
	v_min_u32_e32 v24, v5, v13
	v_max_u32_e32 v25, v5, v13
	v_cndmask_b32_e32 v4, v23, v22, vcc
	v_cndmask_b32_e32 v5, v25, v24, vcc
	s_waitcnt lgkmcnt(4)
	v_min_u32_e32 v22, v6, v14
	v_max_u32_e32 v23, v6, v14
	v_min_u32_e32 v24, v7, v15
	v_max_u32_e32 v25, v7, v15
	v_cndmask_b32_e32 v6, v23, v22, vcc
	v_cndmask_b32_e32 v7, v25, v24, vcc
	s_waitcnt lgkmcnt(2)
	v_min_u32_e32 v22, v8, v16
	v_max_u32_e32 v23, v8, v16
	v_min_u32_e32 v24, v9, v17
	v_max_u32_e32 v25, v9, v17
	v_cndmask_b32_e32 v8, v23, v22, vcc
	v_cndmask_b32_e32 v9, v25, v24, vcc
	s_waitcnt lgkmcnt(0)
	v_min_u32_e32 v22, v10, v18
	v_max_u32_e32 v23, v10, v18
	v_min_u32_e32 v24, v11, v19
	v_max_u32_e32 v25, v11, v19
	v_cndmask_b32_e32 v10, v23, v22, vcc
	v_cndmask_b32_e32 v11, v25, v24, vcc
	v_xor_b32_e32 v21, 2, v20
	v_lshlrev_b32_e32 v21, 2, v21
	ds_bpermute_b32 v12, v21, v4
	ds_bpermute_b32 v13, v21, v5
	ds_bpermute_b32 v14, v21, v6
	ds_bpermute_b32 v15, v21, v7
	ds_bpermute_b32 v16, v21, v8
	ds_bpermute_b32 v17, v21, v9
	ds_bpermute_b32 v18, v21, v10
	ds_bpermute_b32 v19, v21, v11
	v_bfe_u32 v22, v20, 1, 1
	v_bfe_u32 v23, v20, 5, 1
	v_xor_b32_e32 v22, v22, v23
	v_cmp_eq_u32_e32 vcc, 0, v22
	s_waitcnt lgkmcnt(6)
	v_min_u32_e32 v22, v4, v12
	v_max_u32_e32 v23, v4, v12
	v_min_u32_e32 v24, v5, v13
	v_max_u32_e32 v25, v5, v13
	v_cndmask_b32_e32 v4, v23, v22, vcc
	v_cndmask_b32_e32 v5, v25, v24, vcc
	s_waitcnt lgkmcnt(4)
	v_min_u32_e32 v22, v6, v14
	v_max_u32_e32 v23, v6, v14
	v_min_u32_e32 v24, v7, v15
	v_max_u32_e32 v25, v7, v15
	v_cndmask_b32_e32 v6, v23, v22, vcc
	v_cndmask_b32_e32 v7, v25, v24, vcc
	s_waitcnt lgkmcnt(2)
	v_min_u32_e32 v22, v8, v16
	v_max_u32_e32 v23, v8, v16
	v_min_u32_e32 v24, v9, v17
	v_max_u32_e32 v25, v9, v17
	v_cndmask_b32_e32 v8, v23, v22, vcc
	v_cndmask_b32_e32 v9, v25, v24, vcc
	s_waitcnt lgkmcnt(0)
	v_min_u32_e32 v22, v10, v18
	v_max_u32_e32 v23, v10, v18
	v_min_u32_e32 v24, v11, v19
	v_max_u32_e32 v25, v11, v19
	v_cndmask_b32_e32 v10, v23, v22, vcc
	v_cndmask_b32_e32 v11, v25, v24, vcc
	v_xor_b32_e32 v21, 1, v20
	v_lshlrev_b32_e32 v21, 2, v21
	ds_bpermute_b32 v12, v21, v4
	ds_bpermute_b32 v13, v21, v5
	ds_bpermute_b32 v14, v21, v6
	ds_bpermute_b32 v15, v21, v7
	ds_bpermute_b32 v16, v21, v8
	ds_bpermute_b32 v17, v21, v9
	ds_bpermute_b32 v18, v21, v10
	ds_bpermute_b32 v19, v21, v11
	v_bfe_u32 v22, v20, 0, 1
	v_bfe_u32 v23, v20, 5, 1
	v_xor_b32_e32 v22, v22, v23
	v_cmp_eq_u32_e32 vcc, 0, v22
	s_waitcnt lgkmcnt(6)
	v_min_u32_e32 v22, v4, v12
	v_max_u32_e32 v23, v4, v12
	v_min_u32_e32 v24, v5, v13
	v_max_u32_e32 v25, v5, v13
	v_cndmask_b32_e32 v4, v23, v22, vcc
	v_cndmask_b32_e32 v5, v25, v24, vcc
	s_waitcnt lgkmcnt(4)
	v_min_u32_e32 v22, v6, v14
	v_max_u32_e32 v23, v6, v14
	v_min_u32_e32 v24, v7, v15
	v_max_u32_e32 v25, v7, v15
	v_cndmask_b32_e32 v6, v23, v22, vcc
	v_cndmask_b32_e32 v7, v25, v24, vcc
	s_waitcnt lgkmcnt(2)
	v_min_u32_e32 v22, v8, v16
	v_max_u32_e32 v23, v8, v16
	v_min_u32_e32 v24, v9, v17
	v_max_u32_e32 v25, v9, v17
	v_cndmask_b32_e32 v8, v23, v22, vcc
	v_cndmask_b32_e32 v9, v25, v24, vcc
	s_waitcnt lgkmcnt(0)
	v_min_u32_e32 v22, v10, v18
	v_max_u32_e32 v23, v10, v18
	v_min_u32_e32 v24, v11, v19
	v_max_u32_e32 v25, v11, v19
	v_cndmask_b32_e32 v10, v23, v22, vcc
	v_cndmask_b32_e32 v11, v25, v24, vcc
	v_xor_b32_e32 v21, 32, v20
	v_lshlrev_b32_e32 v21, 2, v21
	ds_bpermute_b32 v12, v21, v4
	ds_bpermute_b32 v13, v21, v5
	ds_bpermute_b32 v14, v21, v6
	ds_bpermute_b32 v15, v21, v7
	ds_bpermute_b32 v16, v21, v8
	ds_bpermute_b32 v17, v21, v9
	ds_bpermute_b32 v18, v21, v10
	ds_bpermute_b32 v19, v21, v11
	v_bfe_u32 v22, v20, 5, 1
	v_cmp_eq_u32_e32 vcc, 0, v22
	s_waitcnt lgkmcnt(6)
	v_min_u32_e32 v22, v4, v12
	v_max_u32_e32 v23, v4, v12
	v_min_u32_e32 v24, v5, v13
	v_max_u32_e32 v25, v5, v13
	v_cndmask_b32_e32 v4, v23, v22, vcc
	v_cndmask_b32_e32 v5, v24, v25, vcc
	s_waitcnt lgkmcnt(4)
	v_min_u32_e32 v22, v6, v14
	v_max_u32_e32 v23, v6, v14
	v_min_u32_e32 v24, v7, v15
	v_max_u32_e32 v25, v7, v15
	v_cndmask_b32_e32 v6, v23, v22, vcc
	v_cndmask_b32_e32 v7, v24, v25, vcc
	s_waitcnt lgkmcnt(2)
	v_min_u32_e32 v22, v8, v16
	v_max_u32_e32 v23, v8, v16
	v_min_u32_e32 v24, v9, v17
	v_max_u32_e32 v25, v9, v17
	v_cndmask_b32_e32 v8, v23, v22, vcc
	v_cndmask_b32_e32 v9, v24, v25, vcc
	s_waitcnt lgkmcnt(0)
	v_min_u32_e32 v22, v10, v18
	v_max_u32_e32 v23, v10, v18
	v_min_u32_e32 v24, v11, v19
	v_max_u32_e32 v25, v11, v19
	v_cndmask_b32_e32 v10, v23, v22, vcc
	v_cndmask_b32_e32 v11, v24, v25, vcc
	v_xor_b32_e32 v21, 16, v20
	v_lshlrev_b32_e32 v21, 2, v21
	ds_bpermute_b32 v12, v21, v4
	ds_bpermute_b32 v13, v21, v5
	ds_bpermute_b32 v14, v21, v6
	ds_bpermute_b32 v15, v21, v7
	ds_bpermute_b32 v16, v21, v8
	ds_bpermute_b32 v17, v21, v9
	ds_bpermute_b32 v18, v21, v10
	ds_bpermute_b32 v19, v21, v11
	v_bfe_u32 v22, v20, 4, 1
	v_cmp_eq_u32_e32 vcc, 0, v22
	s_waitcnt lgkmcnt(6)
	v_min_u32_e32 v22, v4, v12
	v_max_u32_e32 v23, v4, v12
	v_min_u32_e32 v24, v5, v13
	v_max_u32_e32 v25, v5, v13
	v_cndmask_b32_e32 v4, v23, v22, vcc
	v_cndmask_b32_e32 v5, v24, v25, vcc
	s_waitcnt lgkmcnt(4)
	v_min_u32_e32 v22, v6, v14
	v_max_u32_e32 v23, v6, v14
	v_min_u32_e32 v24, v7, v15
	v_max_u32_e32 v25, v7, v15
	v_cndmask_b32_e32 v6, v23, v22, vcc
	v_cndmask_b32_e32 v7, v24, v25, vcc
	s_waitcnt lgkmcnt(2)
	v_min_u32_e32 v22, v8, v16
	v_max_u32_e32 v23, v8, v16
	v_min_u32_e32 v24, v9, v17
	v_max_u32_e32 v25, v9, v17
	v_cndmask_b32_e32 v8, v23, v22, vcc
	v_cndmask_b32_e32 v9, v24, v25, vcc
	s_waitcnt lgkmcnt(0)
	v_min_u32_e32 v22, v10, v18
	v_max_u32_e32 v23, v10, v18
	v_min_u32_e32 v24, v11, v19
	v_max_u32_e32 v25, v11, v19
	v_cndmask_b32_e32 v10, v23, v22, vcc
	v_cndmask_b32_e32 v11, v24, v25, vcc
	v_xor_b32_e32 v21, 8, v20
	v_lshlrev_b32_e32 v21, 2, v21
	ds_bpermute_b32 v12, v21, v4
	ds_bpermute_b32 v13, v21, v5
	ds_bpermute_b32 v14, v21, v6
	ds_bpermute_b32 v15, v21, v7
	ds_bpermute_b32 v16, v21, v8
	ds_bpermute_b32 v17, v21, v9
	ds_bpermute_b32 v18, v21, v10
	ds_bpermute_b32 v19, v21, v11
	v_bfe_u32 v22, v20, 3, 1
	v_cmp_eq_u32_e32 vcc, 0, v22
	s_waitcnt lgkmcnt(6)
	v_min_u32_e32 v22, v4, v12
	v_max_u32_e32 v23, v4, v12
	v_min_u32_e32 v24, v5, v13
	v_max_u32_e32 v25, v5, v13
	v_cndmask_b32_e32 v4, v23, v22, vcc
	v_cndmask_b32_e32 v5, v24, v25, vcc
	s_waitcnt lgkmcnt(4)
	v_min_u32_e32 v22, v6, v14
	v_max_u32_e32 v23, v6, v14
	v_min_u32_e32 v24, v7, v15
	v_max_u32_e32 v25, v7, v15
	v_cndmask_b32_e32 v6, v23, v22, vcc
	v_cndmask_b32_e32 v7, v24, v25, vcc
	s_waitcnt lgkmcnt(2)
	v_min_u32_e32 v22, v8, v16
	v_max_u32_e32 v23, v8, v16
	v_min_u32_e32 v24, v9, v17
	v_max_u32_e32 v25, v9, v17
	v_cndmask_b32_e32 v8, v23, v22, vcc
	v_cndmask_b32_e32 v9, v24, v25, vcc
	s_waitcnt lgkmcnt(0)
	v_min_u32_e32 v22, v10, v18
	v_max_u32_e32 v23, v10, v18
	v_min_u32_e32 v24, v11, v19
	v_max_u32_e32 v25, v11, v19
	v_cndmask_b32_e32 v10, v23, v22, vcc
	v_cndmask_b32_e32 v11, v24, v25, vcc
	v_xor_b32_e32 v21, 4, v20
	v_lshlrev_b32_e32 v21, 2, v21
	ds_bpermute_b32 v12, v21, v4
	ds_bpermute_b32 v13, v21, v5
	ds_bpermute_b32 v14, v21, v6
	ds_bpermute_b32 v15, v21, v7
	ds_bpermute_b32 v16, v21, v8
	ds_bpermute_b32 v17, v21, v9
	ds_bpermute_b32 v18, v21, v10
	ds_bpermute_b32 v19, v21, v11
	v_bfe_u32 v22, v20, 2, 1
	v_cmp_eq_u32_e32 vcc, 0, v22
	s_waitcnt lgkmcnt(6)
	v_min_u32_e32 v22, v4, v12
	v_max_u32_e32 v23, v4, v12
	v_min_u32_e32 v24, v5, v13
	v_max_u32_e32 v25, v5, v13
	v_cndmask_b32_e32 v4, v23, v22, vcc
	v_cndmask_b32_e32 v5, v24, v25, vcc
	s_waitcnt lgkmcnt(4)
	v_min_u32_e32 v22, v6, v14
	v_max_u32_e32 v23, v6, v14
	v_min_u32_e32 v24, v7, v15
	v_max_u32_e32 v25, v7, v15
	v_cndmask_b32_e32 v6, v23, v22, vcc
	v_cndmask_b32_e32 v7, v24, v25, vcc
	s_waitcnt lgkmcnt(2)
	v_min_u32_e32 v22, v8, v16
	v_max_u32_e32 v23, v8, v16
	v_min_u32_e32 v24, v9, v17
	v_max_u32_e32 v25, v9, v17
	v_cndmask_b32_e32 v8, v23, v22, vcc
	v_cndmask_b32_e32 v9, v24, v25, vcc
	s_waitcnt lgkmcnt(0)
	v_min_u32_e32 v22, v10, v18
	v_max_u32_e32 v23, v10, v18
	v_min_u32_e32 v24, v11, v19
	v_max_u32_e32 v25, v11, v19
	v_cndmask_b32_e32 v10, v23, v22, vcc
	v_cndmask_b32_e32 v11, v24, v25, vcc
	v_xor_b32_e32 v21, 2, v20
	v_lshlrev_b32_e32 v21, 2, v21
	ds_bpermute_b32 v12, v21, v4
	ds_bpermute_b32 v13, v21, v5
	ds_bpermute_b32 v14, v21, v6
	ds_bpermute_b32 v15, v21, v7
	ds_bpermute_b32 v16, v21, v8
	ds_bpermute_b32 v17, v21, v9
	ds_bpermute_b32 v18, v21, v10
	ds_bpermute_b32 v19, v21, v11
	v_bfe_u32 v22, v20, 1, 1
	v_cmp_eq_u32_e32 vcc, 0, v22
	s_waitcnt lgkmcnt(6)
	v_min_u32_e32 v22, v4, v12
	v_max_u32_e32 v23, v4, v12
	v_min_u32_e32 v24, v5, v13
	v_max_u32_e32 v25, v5, v13
	v_cndmask_b32_e32 v4, v23, v22, vcc
	v_cndmask_b32_e32 v5, v24, v25, vcc
	s_waitcnt lgkmcnt(4)
	v_min_u32_e32 v22, v6, v14
	v_max_u32_e32 v23, v6, v14
	v_min_u32_e32 v24, v7, v15
	v_max_u32_e32 v25, v7, v15
	v_cndmask_b32_e32 v6, v23, v22, vcc
	v_cndmask_b32_e32 v7, v24, v25, vcc
	s_waitcnt lgkmcnt(2)
	v_min_u32_e32 v22, v8, v16
	v_max_u32_e32 v23, v8, v16
	v_min_u32_e32 v24, v9, v17
	v_max_u32_e32 v25, v9, v17
	v_cndmask_b32_e32 v8, v23, v22, vcc
	v_cndmask_b32_e32 v9, v24, v25, vcc
	s_waitcnt lgkmcnt(0)
	v_min_u32_e32 v22, v10, v18
	v_max_u32_e32 v23, v10, v18
	v_min_u32_e32 v24, v11, v19
	v_max_u32_e32 v25, v11, v19
	v_cndmask_b32_e32 v10, v23, v22, vcc
	v_cndmask_b32_e32 v11, v24, v25, vcc
	v_xor_b32_e32 v21, 1, v20
	v_lshlrev_b32_e32 v21, 2, v21
	ds_bpermute_b32 v12, v21, v4
	ds_bpermute_b32 v13, v21, v5
	ds_bpermute_b32 v14, v21, v6
	ds_bpermute_b32 v15, v21, v7
	ds_bpermute_b32 v16, v21, v8
	ds_bpermute_b32 v17, v21, v9
	ds_bpermute_b32 v18, v21, v10
	ds_bpermute_b32 v19, v21, v11
	v_bfe_u32 v22, v20, 0, 1
	v_cmp_eq_u32_e32 vcc, 0, v22
	s_waitcnt lgkmcnt(6)
	v_min_u32_e32 v22, v4, v12
	v_max_u32_e32 v23, v4, v12
	v_min_u32_e32 v24, v5, v13
	v_max_u32_e32 v25, v5, v13
	v_cndmask_b32_e32 v4, v23, v22, vcc
	v_cndmask_b32_e32 v5, v24, v25, vcc
	s_waitcnt lgkmcnt(4)
	v_min_u32_e32 v22, v6, v14
	v_max_u32_e32 v23, v6, v14
	v_min_u32_e32 v24, v7, v15
	v_max_u32_e32 v25, v7, v15
	v_cndmask_b32_e32 v6, v23, v22, vcc
	v_cndmask_b32_e32 v7, v24, v25, vcc
	s_waitcnt lgkmcnt(2)
	v_min_u32_e32 v22, v8, v16
	v_max_u32_e32 v23, v8, v16
	v_min_u32_e32 v24, v9, v17
	v_max_u32_e32 v25, v9, v17
	v_cndmask_b32_e32 v8, v23, v22, vcc
	v_cndmask_b32_e32 v9, v24, v25, vcc
	s_waitcnt lgkmcnt(0)
	v_min_u32_e32 v22, v10, v18
	v_max_u32_e32 v23, v10, v18
	v_min_u32_e32 v24, v11, v19
	v_max_u32_e32 v25, v11, v19
	v_cndmask_b32_e32 v10, v23, v22, vcc
	v_cndmask_b32_e32 v11, v24, v25, vcc
	v_min_u32_e32 v22, v4, v5
	v_max_u32_e32 v5, v4, v5
	v_mov_b32_e32 v4, v22
	v_min_u32_e32 v22, v6, v7
	v_max_u32_e32 v7, v6, v7
	v_mov_b32_e32 v6, v22
	v_min_u32_e32 v22, v8, v9
	v_max_u32_e32 v9, v8, v9
	v_mov_b32_e32 v8, v22
	v_min_u32_e32 v22, v10, v11
	v_max_u32_e32 v11, v10, v11
	v_mov_b32_e32 v10, v22
	v_xor_b32_e32 v21, 32, v20
	v_lshlrev_b32_e32 v21, 2, v21
	ds_bpermute_b32 v12, v21, v4
	ds_bpermute_b32 v13, v21, v5
	ds_bpermute_b32 v14, v21, v6
	ds_bpermute_b32 v15, v21, v7
	ds_bpermute_b32 v16, v21, v8
	ds_bpermute_b32 v17, v21, v9
	ds_bpermute_b32 v18, v21, v10
	ds_bpermute_b32 v19, v21, v11
	v_bfe_u32 v22, v20, 5, 1
	v_cmp_eq_u32_e32 vcc, 0, v22
	s_waitcnt lgkmcnt(6)
	v_min_u32_e32 v22, v4, v12
	v_max_u32_e32 v23, v4, v12
	v_min_u32_e32 v24, v5, v13
	v_max_u32_e32 v25, v5, v13
	v_cndmask_b32_e32 v4, v23, v22, vcc
	v_cndmask_b32_e32 v5, v25, v24, vcc
	s_waitcnt lgkmcnt(4)
	v_min_u32_e32 v22, v6, v14
	v_max_u32_e32 v23, v6, v14
	v_min_u32_e32 v24, v7, v15
	v_max_u32_e32 v25, v7, v15
	v_cndmask_b32_e32 v6, v23, v22, vcc
	v_cndmask_b32_e32 v7, v25, v24, vcc
	s_waitcnt lgkmcnt(2)
	v_min_u32_e32 v22, v8, v16
	v_max_u32_e32 v23, v8, v16
	v_min_u32_e32 v24, v9, v17
	v_max_u32_e32 v25, v9, v17
	v_cndmask_b32_e32 v8, v23, v22, vcc
	v_cndmask_b32_e32 v9, v25, v24, vcc
	s_waitcnt lgkmcnt(0)
	v_min_u32_e32 v22, v10, v18
	v_max_u32_e32 v23, v10, v18
	v_min_u32_e32 v24, v11, v19
	v_max_u32_e32 v25, v11, v19
	v_cndmask_b32_e32 v10, v23, v22, vcc
	v_cndmask_b32_e32 v11, v25, v24, vcc
	v_xor_b32_e32 v21, 16, v20
	v_lshlrev_b32_e32 v21, 2, v21
	ds_bpermute_b32 v12, v21, v4
	ds_bpermute_b32 v13, v21, v5
	ds_bpermute_b32 v14, v21, v6
	ds_bpermute_b32 v15, v21, v7
	ds_bpermute_b32 v16, v21, v8
	ds_bpermute_b32 v17, v21, v9
	ds_bpermute_b32 v18, v21, v10
	ds_bpermute_b32 v19, v21, v11
	v_bfe_u32 v22, v20, 4, 1
	v_cmp_eq_u32_e32 vcc, 0, v22
	s_waitcnt lgkmcnt(6)
	v_min_u32_e32 v22, v4, v12
	v_max_u32_e32 v23, v4, v12
	v_min_u32_e32 v24, v5, v13
	v_max_u32_e32 v25, v5, v13
	v_cndmask_b32_e32 v4, v23, v22, vcc
	v_cndmask_b32_e32 v5, v25, v24, vcc
	s_waitcnt lgkmcnt(4)
	v_min_u32_e32 v22, v6, v14
	v_max_u32_e32 v23, v6, v14
	v_min_u32_e32 v24, v7, v15
	v_max_u32_e32 v25, v7, v15
	v_cndmask_b32_e32 v6, v23, v22, vcc
	v_cndmask_b32_e32 v7, v25, v24, vcc
	s_waitcnt lgkmcnt(2)
	v_min_u32_e32 v22, v8, v16
	v_max_u32_e32 v23, v8, v16
	v_min_u32_e32 v24, v9, v17
	v_max_u32_e32 v25, v9, v17
	v_cndmask_b32_e32 v8, v23, v22, vcc
	v_cndmask_b32_e32 v9, v25, v24, vcc
	s_waitcnt lgkmcnt(0)
	v_min_u32_e32 v22, v10, v18
	v_max_u32_e32 v23, v10, v18
	v_min_u32_e32 v24, v11, v19
	v_max_u32_e32 v25, v11, v19
	v_cndmask_b32_e32 v10, v23, v22, vcc
	v_cndmask_b32_e32 v11, v25, v24, vcc
	v_xor_b32_e32 v21, 8, v20
	v_lshlrev_b32_e32 v21, 2, v21
	ds_bpermute_b32 v12, v21, v4
	ds_bpermute_b32 v13, v21, v5
	ds_bpermute_b32 v14, v21, v6
	ds_bpermute_b32 v15, v21, v7
	ds_bpermute_b32 v16, v21, v8
	ds_bpermute_b32 v17, v21, v9
	ds_bpermute_b32 v18, v21, v10
	ds_bpermute_b32 v19, v21, v11
	v_bfe_u32 v22, v20, 3, 1
	v_cmp_eq_u32_e32 vcc, 0, v22
	s_waitcnt lgkmcnt(6)
	v_min_u32_e32 v22, v4, v12
	v_max_u32_e32 v23, v4, v12
	v_min_u32_e32 v24, v5, v13
	v_max_u32_e32 v25, v5, v13
	v_cndmask_b32_e32 v4, v23, v22, vcc
	v_cndmask_b32_e32 v5, v25, v24, vcc
	s_waitcnt lgkmcnt(4)
	v_min_u32_e32 v22, v6, v14
	v_max_u32_e32 v23, v6, v14
	v_min_u32_e32 v24, v7, v15
	v_max_u32_e32 v25, v7, v15
	v_cndmask_b32_e32 v6, v23, v22, vcc
	v_cndmask_b32_e32 v7, v25, v24, vcc
	s_waitcnt lgkmcnt(2)
	v_min_u32_e32 v22, v8, v16
	v_max_u32_e32 v23, v8, v16
	v_min_u32_e32 v24, v9, v17
	v_max_u32_e32 v25, v9, v17
	v_cndmask_b32_e32 v8, v23, v22, vcc
	v_cndmask_b32_e32 v9, v25, v24, vcc
	s_waitcnt lgkmcnt(0)
	v_min_u32_e32 v22, v10, v18
	v_max_u32_e32 v23, v10, v18
	v_min_u32_e32 v24, v11, v19
	v_max_u32_e32 v25, v11, v19
	v_cndmask_b32_e32 v10, v23, v22, vcc
	v_cndmask_b32_e32 v11, v25, v24, vcc
	v_and_b32_e32 v22, 0x7f, v4
	v_and_b32_e32 v23, 0x7f, v5
	v_lshl_add_u32 v22, v22, 4, v255
	v_lshl_add_u32 v23, v23, 4, v255
	ds_read_b128 v[28:31], v22 offset:0
	ds_read_b128 v[32:35], v23 offset:0
	v_and_b32_e32 v22, 0x7f, v6
	v_and_b32_e32 v23, 0x7f, v7
	v_lshl_add_u32 v22, v22, 4, v255
	v_lshl_add_u32 v23, v23, 4, v255
	ds_read_b128 v[36:39], v22 offset:2048
	ds_read_b128 v[40:43], v23 offset:2048
	v_and_b32_e32 v22, 0x7f, v8
	v_and_b32_e32 v23, 0x7f, v9
	v_lshl_add_u32 v22, v22, 4, v255
	v_lshl_add_u32 v23, v23, 4, v255
	ds_read_b128 v[44:47], v22 offset:4096
	ds_read_b128 v[48:51], v23 offset:4096
	v_and_b32_e32 v22, 0x7f, v10
	v_and_b32_e32 v23, 0x7f, v11
	v_lshl_add_u32 v22, v22, 4, v255
	v_lshl_add_u32 v23, v23, 4, v255
	ds_read_b128 v[52:55], v22 offset:6144
	ds_read_b128 v[56:59], v23 offset:6144
	v_lshl_add_u32 v21, v20, 4, v255
	s_waitcnt lgkmcnt(0)
	ds_write_b128 v21, v[28:31] offset:0
	ds_write_b128 v21, v[32:35] offset:1024
	ds_write_b128 v21, v[36:39] offset:2048
	ds_write_b128 v21, v[40:43] offset:3072
	ds_write_b128 v21, v[44:47] offset:4096
	ds_write_b128 v21, v[48:51] offset:5120
	ds_write_b128 v21, v[52:55] offset:6144
	ds_write_b128 v21, v[56:59] offset:7168
	s_waitcnt lgkmcnt(0)
	v_and_b32_e32 v8, 63, v214
	v_lshl_add_u32 v4, v8, 7, v255
	ds_read_b32 v5, v4
	ds_read_b32 v6, v4 offset:112
	s_waitcnt lgkmcnt(0)
	v_add_u32_e32 v5, v5, v6
	v_lshl_or_b32 v60, v5, 6, v8
	v_xor_b32_e32 v9, 1, v8
	v_lshlrev_b32_e32 v9, 2, v9
	ds_bpermute_b32 v5, v9, v60
	v_bfe_u32 v13, v8, 0, 1
	v_bfe_u32 v10, v8, 1, 1
	v_xor_b32_e32 v13, v13, v10
	v_cmp_eq_u32_e32 vcc, 0, v13
	s_waitcnt lgkmcnt(0)
	v_min_u32_e32 v10, v60, v5
	v_max_u32_e32 v12, v60, v5
	v_cndmask_b32_e32 v60, v12, v10, vcc
	v_xor_b32_e32 v9, 2, v8
	v_lshlrev_b32_e32 v9, 2, v9
	ds_bpermute_b32 v5, v9, v60
	v_bfe_u32 v13, v8, 1, 1
	v_bfe_u32 v10, v8, 2, 1
	v_xor_b32_e32 v13, v13, v10
	v_cmp_eq_u32_e32 vcc, 0, v13
	s_waitcnt lgkmcnt(0)
	v_min_u32_e32 v10, v60, v5
	v_max_u32_e32 v12, v60, v5
	v_cndmask_b32_e32 v60, v12, v10, vcc
	v_xor_b32_e32 v9, 1, v8
	v_lshlrev_b32_e32 v9, 2, v9
	ds_bpermute_b32 v5, v9, v60
	v_bfe_u32 v13, v8, 0, 1
	v_bfe_u32 v10, v8, 2, 1
	v_xor_b32_e32 v13, v13, v10
	v_cmp_eq_u32_e32 vcc, 0, v13
	s_waitcnt lgkmcnt(0)
	v_min_u32_e32 v10, v60, v5
	v_max_u32_e32 v12, v60, v5
	v_cndmask_b32_e32 v60, v12, v10, vcc
	v_xor_b32_e32 v9, 4, v8
	v_lshlrev_b32_e32 v9, 2, v9
	ds_bpermute_b32 v5, v9, v60
	v_bfe_u32 v13, v8, 2, 1
	v_bfe_u32 v10, v8, 3, 1
	v_xor_b32_e32 v13, v13, v10
	v_cmp_eq_u32_e32 vcc, 0, v13
	s_waitcnt lgkmcnt(0)
	v_min_u32_e32 v10, v60, v5
	v_max_u32_e32 v12, v60, v5
	v_cndmask_b32_e32 v60, v12, v10, vcc
	v_xor_b32_e32 v9, 2, v8
	v_lshlrev_b32_e32 v9, 2, v9
	ds_bpermute_b32 v5, v9, v60
	v_bfe_u32 v13, v8, 1, 1
	v_bfe_u32 v10, v8, 3, 1
	v_xor_b32_e32 v13, v13, v10
	v_cmp_eq_u32_e32 vcc, 0, v13
	s_waitcnt lgkmcnt(0)
	v_min_u32_e32 v10, v60, v5
	v_max_u32_e32 v12, v60, v5
	v_cndmask_b32_e32 v60, v12, v10, vcc
	v_xor_b32_e32 v9, 1, v8
	v_lshlrev_b32_e32 v9, 2, v9
	ds_bpermute_b32 v5, v9, v60
	v_bfe_u32 v13, v8, 0, 1
	v_bfe_u32 v10, v8, 3, 1
	v_xor_b32_e32 v13, v13, v10
	v_cmp_eq_u32_e32 vcc, 0, v13
	s_waitcnt lgkmcnt(0)
	v_min_u32_e32 v10, v60, v5
	v_max_u32_e32 v12, v60, v5
	v_cndmask_b32_e32 v60, v12, v10, vcc
	v_xor_b32_e32 v9, 8, v8
	v_lshlrev_b32_e32 v9, 2, v9
	ds_bpermute_b32 v5, v9, v60
	v_bfe_u32 v13, v8, 3, 1
	v_bfe_u32 v10, v8, 4, 1
	v_xor_b32_e32 v13, v13, v10
	v_cmp_eq_u32_e32 vcc, 0, v13
	s_waitcnt lgkmcnt(0)
	v_min_u32_e32 v10, v60, v5
	v_max_u32_e32 v12, v60, v5
	v_cndmask_b32_e32 v60, v12, v10, vcc
	v_xor_b32_e32 v9, 4, v8
	v_lshlrev_b32_e32 v9, 2, v9
	ds_bpermute_b32 v5, v9, v60
	v_bfe_u32 v13, v8, 2, 1
	v_bfe_u32 v10, v8, 4, 1
	v_xor_b32_e32 v13, v13, v10
	v_cmp_eq_u32_e32 vcc, 0, v13
	s_waitcnt lgkmcnt(0)
	v_min_u32_e32 v10, v60, v5
	v_max_u32_e32 v12, v60, v5
	v_cndmask_b32_e32 v60, v12, v10, vcc
	v_xor_b32_e32 v9, 2, v8
	v_lshlrev_b32_e32 v9, 2, v9
	ds_bpermute_b32 v5, v9, v60
	v_bfe_u32 v13, v8, 1, 1
	v_bfe_u32 v10, v8, 4, 1
	v_xor_b32_e32 v13, v13, v10
	v_cmp_eq_u32_e32 vcc, 0, v13
	s_waitcnt lgkmcnt(0)
	v_min_u32_e32 v10, v60, v5
	v_max_u32_e32 v12, v60, v5
	v_cndmask_b32_e32 v60, v12, v10, vcc
	v_xor_b32_e32 v9, 1, v8
	v_lshlrev_b32_e32 v9, 2, v9
	ds_bpermute_b32 v5, v9, v60
	v_bfe_u32 v13, v8, 0, 1
	v_bfe_u32 v10, v8, 4, 1
	v_xor_b32_e32 v13, v13, v10
	v_cmp_eq_u32_e32 vcc, 0, v13
	s_waitcnt lgkmcnt(0)
	v_min_u32_e32 v10, v60, v5
	v_max_u32_e32 v12, v60, v5
	v_cndmask_b32_e32 v60, v12, v10, vcc
	v_xor_b32_e32 v9, 16, v8
	v_lshlrev_b32_e32 v9, 2, v9
	ds_bpermute_b32 v5, v9, v60
	v_bfe_u32 v13, v8, 4, 1
	v_bfe_u32 v10, v8, 5, 1
	v_xor_b32_e32 v13, v13, v10
	v_cmp_eq_u32_e32 vcc, 0, v13
	s_waitcnt lgkmcnt(0)
	v_min_u32_e32 v10, v60, v5
	v_max_u32_e32 v12, v60, v5
	v_cndmask_b32_e32 v60, v12, v10, vcc
	v_xor_b32_e32 v9, 8, v8
	v_lshlrev_b32_e32 v9, 2, v9
	ds_bpermute_b32 v5, v9, v60
	v_bfe_u32 v13, v8, 3, 1
	v_bfe_u32 v10, v8, 5, 1
	v_xor_b32_e32 v13, v13, v10
	v_cmp_eq_u32_e32 vcc, 0, v13
	s_waitcnt lgkmcnt(0)
	v_min_u32_e32 v10, v60, v5
	v_max_u32_e32 v12, v60, v5
	v_cndmask_b32_e32 v60, v12, v10, vcc
	v_xor_b32_e32 v9, 4, v8
	v_lshlrev_b32_e32 v9, 2, v9
	ds_bpermute_b32 v5, v9, v60
	v_bfe_u32 v13, v8, 2, 1
	v_bfe_u32 v10, v8, 5, 1
	v_xor_b32_e32 v13, v13, v10
	v_cmp_eq_u32_e32 vcc, 0, v13
	s_waitcnt lgkmcnt(0)
	v_min_u32_e32 v10, v60, v5
	v_max_u32_e32 v12, v60, v5
	v_cndmask_b32_e32 v60, v12, v10, vcc
	v_xor_b32_e32 v9, 2, v8
	v_lshlrev_b32_e32 v9, 2, v9
	ds_bpermute_b32 v5, v9, v60
	v_bfe_u32 v13, v8, 1, 1
	v_bfe_u32 v10, v8, 5, 1
	v_xor_b32_e32 v13, v13, v10
	v_cmp_eq_u32_e32 vcc, 0, v13
	s_waitcnt lgkmcnt(0)
	v_min_u32_e32 v10, v60, v5
	v_max_u32_e32 v12, v60, v5
	v_cndmask_b32_e32 v60, v12, v10, vcc
	v_xor_b32_e32 v9, 1, v8
	v_lshlrev_b32_e32 v9, 2, v9
	ds_bpermute_b32 v5, v9, v60
	v_bfe_u32 v13, v8, 0, 1
	v_bfe_u32 v10, v8, 5, 1
	v_xor_b32_e32 v13, v13, v10
	v_cmp_eq_u32_e32 vcc, 0, v13
	s_waitcnt lgkmcnt(0)
	v_min_u32_e32 v10, v60, v5
	v_max_u32_e32 v12, v60, v5
	v_cndmask_b32_e32 v60, v12, v10, vcc
	v_xor_b32_e32 v9, 32, v8
	v_lshlrev_b32_e32 v9, 2, v9
	ds_bpermute_b32 v5, v9, v60
	v_bfe_u32 v13, v8, 5, 1
	v_cmp_eq_u32_e32 vcc, 0, v13
	s_waitcnt lgkmcnt(0)
	v_min_u32_e32 v10, v60, v5
	v_max_u32_e32 v12, v60, v5
	v_cndmask_b32_e32 v60, v12, v10, vcc
	v_xor_b32_e32 v9, 16, v8
	v_lshlrev_b32_e32 v9, 2, v9
	ds_bpermute_b32 v5, v9, v60
	v_bfe_u32 v13, v8, 4, 1
	v_cmp_eq_u32_e32 vcc, 0, v13
	s_waitcnt lgkmcnt(0)
	v_min_u32_e32 v10, v60, v5
	v_max_u32_e32 v12, v60, v5
	v_cndmask_b32_e32 v60, v12, v10, vcc
	v_xor_b32_e32 v9, 8, v8
	v_lshlrev_b32_e32 v9, 2, v9
	ds_bpermute_b32 v5, v9, v60
	v_bfe_u32 v13, v8, 3, 1
	v_cmp_eq_u32_e32 vcc, 0, v13
	s_waitcnt lgkmcnt(0)
	v_min_u32_e32 v10, v60, v5
	v_max_u32_e32 v12, v60, v5
	v_cndmask_b32_e32 v60, v12, v10, vcc
	v_xor_b32_e32 v9, 4, v8
	v_lshlrev_b32_e32 v9, 2, v9
	ds_bpermute_b32 v5, v9, v60
	v_bfe_u32 v13, v8, 2, 1
	v_cmp_eq_u32_e32 vcc, 0, v13
	s_waitcnt lgkmcnt(0)
	v_min_u32_e32 v10, v60, v5
	v_max_u32_e32 v12, v60, v5
	v_cndmask_b32_e32 v60, v12, v10, vcc
	v_xor_b32_e32 v9, 2, v8
	v_lshlrev_b32_e32 v9, 2, v9
	ds_bpermute_b32 v5, v9, v60
	v_bfe_u32 v13, v8, 1, 1
	v_cmp_eq_u32_e32 vcc, 0, v13
	s_waitcnt lgkmcnt(0)
	v_min_u32_e32 v10, v60, v5
	v_max_u32_e32 v12, v60, v5
	v_cndmask_b32_e32 v60, v12, v10, vcc
	v_xor_b32_e32 v9, 1, v8
	v_lshlrev_b32_e32 v9, 2, v9
	ds_bpermute_b32 v5, v9, v60
	v_bfe_u32 v13, v8, 0, 1
	v_cmp_eq_u32_e32 vcc, 0, v13
	s_waitcnt lgkmcnt(0)
	v_min_u32_e32 v10, v60, v5
	v_max_u32_e32 v12, v60, v5
	v_cndmask_b32_e32 v60, v12, v10, vcc
	s_waitcnt vmcnt(0)
	v_mov_b32_e32 v92, v216
	v_mov_b32_e32 v93, v217
	v_mov_b32_e32 v94, v218
	v_mov_b32_e32 v95, v219
	v_mov_b32_e32 v96, v220
	v_mov_b32_e32 v97, v221
	v_mov_b32_e32 v98, v222
	v_mov_b32_e32 v99, v223
	v_mov_b32_e32 v100, v224
	v_mov_b32_e32 v101, v225
	v_mov_b32_e32 v102, v226
	v_mov_b32_e32 v103, v227
	v_mov_b32_e32 v104, v228
	v_mov_b32_e32 v105, v229
	v_mov_b32_e32 v106, v230
	v_mov_b32_e32 v107, v231
	v_mov_b32_e32 v216, v232
	v_mov_b32_e32 v217, v233
	v_mov_b32_e32 v218, v234
	v_mov_b32_e32 v219, v235
	v_mov_b32_e32 v220, v236
	v_mov_b32_e32 v221, v237
	v_mov_b32_e32 v222, v238
	v_mov_b32_e32 v223, v239
	v_mov_b32_e32 v224, v240
	v_mov_b32_e32 v225, v241
	v_mov_b32_e32 v226, v242
	v_mov_b32_e32 v227, v243
	v_mov_b32_e32 v228, v244
	v_mov_b32_e32 v229, v245
	v_mov_b32_e32 v230, v246
	v_mov_b32_e32 v231, v247
	v_mov_b32_e32 v108, 0
	v_mov_b32_e32 v109, 0
	v_mov_b32_e32 v110, 0
	v_mov_b32_e32 v111, 0
	v_mov_b32_e32 v112, 0
	v_mov_b32_e32 v113, 0
	v_mov_b32_e32 v114, 0
	v_mov_b32_e32 v115, 0
	v_mov_b32_e32 v116, 0
	v_mov_b32_e32 v117, 0
	v_mov_b32_e32 v118, 0
	v_mov_b32_e32 v119, 0
	v_mov_b32_e32 v120, 0
	v_mov_b32_e32 v121, 0
	v_mov_b32_e32 v122, 0
	v_mov_b32_e32 v123, 0
	v_mov_b32_e32 v124, 0
	v_mov_b32_e32 v125, 0
	v_mov_b32_e32 v126, 0
	v_mov_b32_e32 v127, 0
	v_mov_b32_e32 v128, 0
	v_mov_b32_e32 v129, 0
	v_mov_b32_e32 v130, 0
	v_mov_b32_e32 v131, 0
	v_mov_b32_e32 v132, 0
	v_mov_b32_e32 v133, 0
	v_mov_b32_e32 v136, 0
	v_mov_b32_e32 v137, 0
	v_mov_b32_e32 v138, 0
	v_mov_b32_e32 v139, 0
	v_mov_b32_e32 v140, 0
	v_mov_b32_e32 v141, 0
	v_mov_b32_e32 v188, 0
	v_mov_b32_e32 v189, 0
	v_mov_b32_e32 v190, 0
	v_mov_b32_e32 v191, 0
	v_mov_b32_e32 v192, 0
	v_mov_b32_e32 v193, 0
	v_mov_b32_e32 v194, 0
	v_mov_b32_e32 v195, 0
	v_mov_b32_e32 v196, 0
	v_mov_b32_e32 v197, 0
	v_mov_b32_e32 v198, 0
	v_mov_b32_e32 v199, 0
	v_mov_b32_e32 v200, 0
	v_mov_b32_e32 v201, 0
	v_mov_b32_e32 v202, 0
	v_mov_b32_e32 v203, 0
	v_mov_b32_e32 v204, 0
	v_mov_b32_e32 v205, 0
	v_mov_b32_e32 v206, 0
	v_mov_b32_e32 v207, 0
	v_mov_b32_e32 v208, 0
	v_mov_b32_e32 v209, 0
	v_mov_b32_e32 v210, 0
	v_mov_b32_e32 v211, 0
	v_mov_b32_e32 v212, 0
	v_mov_b32_e32 v213, 0
	v_mov_b32_e32 v186, 0
	v_mov_b32_e32 v187, 0
	v_mov_b32_e32 v66, 0
	v_mov_b32_e32 v67, 0
	v_mov_b32_e32 v68, 0
	v_mov_b32_e32 v69, 0
	v_lshl_add_u32 v61, v215, 4, v255
	s_mov_b32 s71, 0
	s_mov_b32 s4, 0
	v_readlane_b32 s14, v60, s4
	s_and_b32 s14, s14, 63
	v_lshl_add_u32 v0, s14, 7, v61
	ds_read_b128 v[56:59], v0
	s_waitcnt lgkmcnt(0)
	v_readlane_b32 s5, v56, 0
	s_lshl_b32 s52, s5, 10
	s_add_u32 s56, s98, s52
	s_addc_u32 s57, s99, 0
	global_load_dwordx4 v[4:7], v62, s[56:57]
	v_readlane_b32 s6, v56, 32
	s_lshl_b32 s52, s6, 10
	s_add_u32 s56, s98, s52
	s_addc_u32 s57, s99, 0
	global_load_dwordx4 v[8:11], v62, s[56:57]
	v_readlane_b32 s7, v56, 16
	s_lshl_b32 s52, s7, 10
	s_add_u32 s56, s98, s52
	s_addc_u32 s57, s99, 0
	global_load_dwordx4 v[12:15], v62, s[56:57]
	v_readlane_b32 s8, v56, 48
	s_lshl_b32 s52, s8, 10
	s_add_u32 s56, s98, s52
	s_addc_u32 s57, s99, 0
	global_load_dwordx4 v[16:19], v62, s[56:57]
	v_readlane_b32 s9, v56, 8
	s_lshl_b32 s52, s9, 10
	s_add_u32 s56, s98, s52
	s_addc_u32 s57, s99, 0
	global_load_dwordx4 v[20:23], v62, s[56:57]
	v_readlane_b32 s11, v56, 40
	s_lshl_b32 s52, s11, 10
	s_add_u32 s56, s98, s52
	s_addc_u32 s57, s99, 0
	global_load_dwordx4 v[24:27], v62, s[56:57]
	v_readlane_b32 s13, v56, 24
	s_lshl_b32 s52, s13, 10
	s_add_u32 s56, s98, s52
	s_addc_u32 s57, s99, 0
	global_load_dwordx4 v[28:31], v62, s[56:57]
	v_readlane_b32 s16, v56, 56
	s_lshl_b32 s52, s16, 10
	s_add_u32 s56, s98, s52
	s_addc_u32 s57, s99, 0
	global_load_dwordx4 v[32:35], v62, s[56:57]
	s_lshl_b32 s52, s5, 9
	s_add_u32 s58, s100, s52
	s_addc_u32 s59, s101, 0
	global_load_dwordx2 v[36:37], v63, s[58:59]
	s_lshl_b32 s52, s6, 9
	s_add_u32 s58, s100, s52
	s_addc_u32 s59, s101, 0
	global_load_dwordx2 v[38:39], v63, s[58:59]
	s_lshl_b32 s52, s7, 9
	s_add_u32 s58, s100, s52
	s_addc_u32 s59, s101, 0
	global_load_dwordx2 v[40:41], v63, s[58:59]
	s_lshl_b32 s52, s8, 9
	s_add_u32 s58, s100, s52
	s_addc_u32 s59, s101, 0
	global_load_dwordx2 v[42:43], v63, s[58:59]
	s_lshl_b32 s52, s9, 9
	s_add_u32 s58, s100, s52
	s_addc_u32 s59, s101, 0
	global_load_dwordx2 v[44:45], v63, s[58:59]
	s_lshl_b32 s52, s11, 9
	s_add_u32 s58, s100, s52
	s_addc_u32 s59, s101, 0
	global_load_dwordx2 v[46:47], v63, s[58:59]
	s_lshl_b32 s52, s13, 9
	s_add_u32 s58, s100, s52
	s_addc_u32 s59, s101, 0
	global_load_dwordx2 v[48:49], v63, s[58:59]
	s_lshl_b32 s52, s16, 9
	s_add_u32 s58, s100, s52
	s_addc_u32 s59, s101, 0
	global_load_dwordx2 v[50:51], v63, s[58:59]
	v_mov_b32_e32 v52, v56
	v_mov_b32_e32 v53, v57
	v_mov_b32_e32 v54, v58
	v_mov_b32_e32 v55, v59
	s_lshr_b32 s15, s14, 4
.Lex_grp:
	s_add_i32 s17, s4, 1
	s_min_u32 s17, s17, 63
	v_readlane_b32 s14, v60, s17
	s_and_b32 s14, s14, 63
	v_lshl_add_u32 v0, s14, 7, v61
	ds_read_b128 v[56:59], v0
	s_waitcnt lgkmcnt(0)
	s_cmp_lg_u32 s15, 0
	s_cbranch_scc1 .Lex_d1
	s_waitcnt vmcnt(14)
	v_cvt_scalef32_pk_bf16_fp8 v156, v4, 1.0
	v_cvt_scalef32_pk_bf16_fp8 v157, v4, 1.0 op_sel:[1,0,0]
	v_cvt_scalef32_pk_bf16_fp8 v158, v5, 1.0
	v_cvt_scalef32_pk_bf16_fp8 v159, v5, 1.0 op_sel:[1,0,0]
	v_cvt_scalef32_pk_bf16_fp8 v160, v6, 1.0
	v_cvt_scalef32_pk_bf16_fp8 v161, v6, 1.0 op_sel:[1,0,0]
	v_cvt_scalef32_pk_bf16_fp8 v162, v7, 1.0
	v_cvt_scalef32_pk_bf16_fp8 v163, v7, 1.0 op_sel:[1,0,0]
	v_cvt_scalef32_pk_bf16_fp8 v164, v8, 1.0
	v_cvt_scalef32_pk_bf16_fp8 v165, v8, 1.0 op_sel:[1,0,0]
	v_cvt_scalef32_pk_bf16_fp8 v166, v9, 1.0
	v_cvt_scalef32_pk_bf16_fp8 v167, v9, 1.0 op_sel:[1,0,0]
	v_cvt_scalef32_pk_bf16_fp8 v168, v10, 1.0
	v_cvt_scalef32_pk_bf16_fp8 v169, v10, 1.0 op_sel:[1,0,0]
	v_cvt_scalef32_pk_bf16_fp8 v170, v11, 1.0
	v_cvt_scalef32_pk_bf16_fp8 v171, v11, 1.0 op_sel:[1,0,0]
	v_dot2_f32_bf16 v240, v156, v92, 0
	v_dot2_f32_bf16 v241, v164, v92, 0
	v_dot2c_f32_bf16_e32 v240, v157, v93
	v_dot2c_f32_bf16_e32 v241, v165, v93
	v_dot2c_f32_bf16_e32 v240, v158, v94
	v_dot2c_f32_bf16_e32 v241, v166, v94
	v_dot2c_f32_bf16_e32 v240, v159, v95
	v_dot2c_f32_bf16_e32 v241, v167, v95
	v_dot2c_f32_bf16_e32 v240, v160, v96
	v_dot2c_f32_bf16_e32 v241, v168, v96
	v_dot2c_f32_bf16_e32 v240, v161, v97
	v_dot2c_f32_bf16_e32 v241, v169, v97
	v_dot2c_f32_bf16_e32 v240, v162, v98
	v_dot2c_f32_bf16_e32 v241, v170, v98
	v_dot2c_f32_bf16_e32 v240, v163, v99
	v_dot2c_f32_bf16_e32 v241, v171, v99
	v_readlane_b32 s5, v56, 0
	s_lshl_b32 s52, s5, 10
	s_add_u32 s56, s98, s52
	s_addc_u32 s57, s99, 0
	global_load_dwordx4 v[4:7], v62, s[56:57]
	v_readlane_b32 s6, v56, 32
	s_lshl_b32 s52, s6, 10
	s_add_u32 s56, s98, s52
	s_addc_u32 s57, s99, 0
	global_load_dwordx4 v[8:11], v62, s[56:57]
	s_waitcnt vmcnt(14)
	v_cvt_scalef32_pk_bf16_fp8 v156, v12, 1.0
	v_cvt_scalef32_pk_bf16_fp8 v157, v12, 1.0 op_sel:[1,0,0]
	v_cvt_scalef32_pk_bf16_fp8 v158, v13, 1.0
	v_cvt_scalef32_pk_bf16_fp8 v159, v13, 1.0 op_sel:[1,0,0]
	v_cvt_scalef32_pk_bf16_fp8 v160, v14, 1.0
	v_cvt_scalef32_pk_bf16_fp8 v161, v14, 1.0 op_sel:[1,0,0]
	v_cvt_scalef32_pk_bf16_fp8 v162, v15, 1.0
	v_cvt_scalef32_pk_bf16_fp8 v163, v15, 1.0 op_sel:[1,0,0]
	v_cvt_scalef32_pk_bf16_fp8 v164, v16, 1.0
	v_cvt_scalef32_pk_bf16_fp8 v165, v16, 1.0 op_sel:[1,0,0]
	v_cvt_scalef32_pk_bf16_fp8 v166, v17, 1.0
	v_cvt_scalef32_pk_bf16_fp8 v167, v17, 1.0 op_sel:[1,0,0]
	v_cvt_scalef32_pk_bf16_fp8 v168, v18, 1.0
	v_cvt_scalef32_pk_bf16_fp8 v169, v18, 1.0 op_sel:[1,0,0]
	v_cvt_scalef32_pk_bf16_fp8 v170, v19, 1.0
	v_cvt_scalef32_pk_bf16_fp8 v171, v19, 1.0 op_sel:[1,0,0]
	v_dot2_f32_bf16 v242, v156, v92, 0
	v_dot2_f32_bf16 v243, v164, v92, 0
	v_dot2c_f32_bf16_e32 v242, v157, v93
	v_dot2c_f32_bf16_e32 v243, v165, v93
	v_dot2c_f32_bf16_e32 v242, v158, v94
	v_dot2c_f32_bf16_e32 v243, v166, v94
	v_dot2c_f32_bf16_e32 v242, v159, v95
	v_dot2c_f32_bf16_e32 v243, v167, v95
	v_dot2c_f32_bf16_e32 v242, v160, v96
	v_dot2c_f32_bf16_e32 v243, v168, v96
	v_dot2c_f32_bf16_e32 v242, v161, v97
	v_dot2c_f32_bf16_e32 v243, v169, v97
	v_dot2c_f32_bf16_e32 v242, v162, v98
	v_dot2c_f32_bf16_e32 v243, v170, v98
	v_dot2c_f32_bf16_e32 v242, v163, v99
	v_dot2c_f32_bf16_e32 v243, v171, v99
	v_readlane_b32 s7, v56, 16
	s_lshl_b32 s52, s7, 10
	s_add_u32 s56, s98, s52
	s_addc_u32 s57, s99, 0
	global_load_dwordx4 v[12:15], v62, s[56:57]
	v_readlane_b32 s8, v56, 48
	s_lshl_b32 s52, s8, 10
	s_add_u32 s56, s98, s52
	s_addc_u32 s57, s99, 0
	global_load_dwordx4 v[16:19], v62, s[56:57]
	s_waitcnt vmcnt(14)
	v_cvt_scalef32_pk_bf16_fp8 v156, v20, 1.0
	v_cvt_scalef32_pk_bf16_fp8 v157, v20, 1.0 op_sel:[1,0,0]
	v_cvt_scalef32_pk_bf16_fp8 v158, v21, 1.0
	v_cvt_scalef32_pk_bf16_fp8 v159, v21, 1.0 op_sel:[1,0,0]
	v_cvt_scalef32_pk_bf16_fp8 v160, v22, 1.0
	v_cvt_scalef32_pk_bf16_fp8 v161, v22, 1.0 op_sel:[1,0,0]
	v_cvt_scalef32_pk_bf16_fp8 v162, v23, 1.0
	v_cvt_scalef32_pk_bf16_fp8 v163, v23, 1.0 op_sel:[1,0,0]
	v_cvt_scalef32_pk_bf16_fp8 v164, v24, 1.0
	v_cvt_scalef32_pk_bf16_fp8 v165, v24, 1.0 op_sel:[1,0,0]
	v_cvt_scalef32_pk_bf16_fp8 v166, v25, 1.0
	v_cvt_scalef32_pk_bf16_fp8 v167, v25, 1.0 op_sel:[1,0,0]
	v_cvt_scalef32_pk_bf16_fp8 v168, v26, 1.0
	v_cvt_scalef32_pk_bf16_fp8 v169, v26, 1.0 op_sel:[1,0,0]
	v_cvt_scalef32_pk_bf16_fp8 v170, v27, 1.0
	v_cvt_scalef32_pk_bf16_fp8 v171, v27, 1.0 op_sel:[1,0,0]
	v_dot2_f32_bf16 v244, v156, v92, 0
	v_dot2_f32_bf16 v245, v164, v92, 0
	v_dot2c_f32_bf16_e32 v244, v157, v93
	v_dot2c_f32_bf16_e32 v245, v165, v93
	v_dot2c_f32_bf16_e32 v244, v158, v94
	v_dot2c_f32_bf16_e32 v245, v166, v94
	v_dot2c_f32_bf16_e32 v244, v159, v95
	v_dot2c_f32_bf16_e32 v245, v167, v95
	v_dot2c_f32_bf16_e32 v244, v160, v96
	v_dot2c_f32_bf16_e32 v245, v168, v96
	v_dot2c_f32_bf16_e32 v244, v161, v97
	v_dot2c_f32_bf16_e32 v245, v169, v97
	v_dot2c_f32_bf16_e32 v244, v162, v98
	v_dot2c_f32_bf16_e32 v245, v170, v98
	v_dot2c_f32_bf16_e32 v244, v163, v99
	v_dot2c_f32_bf16_e32 v245, v171, v99
	v_readlane_b32 s9, v56, 8
	s_lshl_b32 s52, s9, 10
	s_add_u32 s56, s98, s52
	s_addc_u32 s57, s99, 0
	global_load_dwordx4 v[20:23], v62, s[56:57]
	v_readlane_b32 s11, v56, 40
	s_lshl_b32 s52, s11, 10
	s_add_u32 s56, s98, s52
	s_addc_u32 s57, s99, 0
	global_load_dwordx4 v[24:27], v62, s[56:57]
	s_waitcnt vmcnt(14)
	v_cvt_scalef32_pk_bf16_fp8 v156, v28, 1.0
	v_cvt_scalef32_pk_bf16_fp8 v157, v28, 1.0 op_sel:[1,0,0]
	v_cvt_scalef32_pk_bf16_fp8 v158, v29, 1.0
	v_cvt_scalef32_pk_bf16_fp8 v159, v29, 1.0 op_sel:[1,0,0]
	v_cvt_scalef32_pk_bf16_fp8 v160, v30, 1.0
	v_cvt_scalef32_pk_bf16_fp8 v161, v30, 1.0 op_sel:[1,0,0]
	v_cvt_scalef32_pk_bf16_fp8 v162, v31, 1.0
	v_cvt_scalef32_pk_bf16_fp8 v163, v31, 1.0 op_sel:[1,0,0]
	v_cvt_scalef32_pk_bf16_fp8 v164, v32, 1.0
	v_cvt_scalef32_pk_bf16_fp8 v165, v32, 1.0 op_sel:[1,0,0]
	v_cvt_scalef32_pk_bf16_fp8 v166, v33, 1.0
	v_cvt_scalef32_pk_bf16_fp8 v167, v33, 1.0 op_sel:[1,0,0]
	v_cvt_scalef32_pk_bf16_fp8 v168, v34, 1.0
	v_cvt_scalef32_pk_bf16_fp8 v169, v34, 1.0 op_sel:[1,0,0]
	v_cvt_scalef32_pk_bf16_fp8 v170, v35, 1.0
	v_cvt_scalef32_pk_bf16_fp8 v171, v35, 1.0 op_sel:[1,0,0]
	v_dot2_f32_bf16 v246, v156, v92, 0
	v_dot2_f32_bf16 v247, v164, v92, 0
	v_dot2c_f32_bf16_e32 v246, v157, v93
	v_dot2c_f32_bf16_e32 v247, v165, v93
	v_dot2c_f32_bf16_e32 v246, v158, v94
	v_dot2c_f32_bf16_e32 v247, v166, v94
	v_dot2c_f32_bf16_e32 v246, v159, v95
	v_dot2c_f32_bf16_e32 v247, v167, v95
	v_dot2c_f32_bf16_e32 v246, v160, v96
	v_dot2c_f32_bf16_e32 v247, v168, v96
	v_dot2c_f32_bf16_e32 v246, v161, v97
	v_dot2c_f32_bf16_e32 v247, v169, v97
	v_dot2c_f32_bf16_e32 v246, v162, v98
	v_dot2c_f32_bf16_e32 v247, v170, v98
	v_dot2c_f32_bf16_e32 v246, v163, v99
	v_dot2c_f32_bf16_e32 v247, v171, v99
	v_readlane_b32 s13, v56, 24
	s_lshl_b32 s52, s13, 10
	s_add_u32 s56, s98, s52
	s_addc_u32 s57, s99, 0
	global_load_dwordx4 v[28:31], v62, s[56:57]
	v_readlane_b32 s16, v56, 56
	s_lshl_b32 s52, s16, 10
	s_add_u32 s56, s98, s52
	s_addc_u32 s57, s99, 0
	global_load_dwordx4 v[32:35], v62, s[56:57]
	s_branch .Lex_d4
.Lex_d1:
	s_cmp_lg_u32 s15, 1
	s_cbranch_scc1 .Lex_d2
	s_waitcnt vmcnt(14)
	v_cvt_scalef32_pk_bf16_fp8 v156, v4, 1.0
	v_cvt_scalef32_pk_bf16_fp8 v157, v4, 1.0 op_sel:[1,0,0]
	v_cvt_scalef32_pk_bf16_fp8 v158, v5, 1.0
	v_cvt_scalef32_pk_bf16_fp8 v159, v5, 1.0 op_sel:[1,0,0]
	v_cvt_scalef32_pk_bf16_fp8 v160, v6, 1.0
	v_cvt_scalef32_pk_bf16_fp8 v161, v6, 1.0 op_sel:[1,0,0]
	v_cvt_scalef32_pk_bf16_fp8 v162, v7, 1.0
	v_cvt_scalef32_pk_bf16_fp8 v163, v7, 1.0 op_sel:[1,0,0]
	v_cvt_scalef32_pk_bf16_fp8 v164, v8, 1.0
	v_cvt_scalef32_pk_bf16_fp8 v165, v8, 1.0 op_sel:[1,0,0]
	v_cvt_scalef32_pk_bf16_fp8 v166, v9, 1.0
	v_cvt_scalef32_pk_bf16_fp8 v167, v9, 1.0 op_sel:[1,0,0]
	v_cvt_scalef32_pk_bf16_fp8 v168, v10, 1.0
	v_cvt_scalef32_pk_bf16_fp8 v169, v10, 1.0 op_sel:[1,0,0]
	v_cvt_scalef32_pk_bf16_fp8 v170, v11, 1.0
	v_cvt_scalef32_pk_bf16_fp8 v171, v11, 1.0 op_sel:[1,0,0]
	v_dot2_f32_bf16 v240, v156, v100, 0
	v_dot2_f32_bf16 v241, v164, v100, 0
	v_dot2c_f32_bf16_e32 v240, v157, v101
	v_dot2c_f32_bf16_e32 v241, v165, v101
	v_dot2c_f32_bf16_e32 v240, v158, v102
	v_dot2c_f32_bf16_e32 v241, v166, v102
	v_dot2c_f32_bf16_e32 v240, v159, v103
	v_dot2c_f32_bf16_e32 v241, v167, v103
	v_dot2c_f32_bf16_e32 v240, v160, v104
	v_dot2c_f32_bf16_e32 v241, v168, v104
	v_dot2c_f32_bf16_e32 v240, v161, v105
	v_dot2c_f32_bf16_e32 v241, v169, v105
	v_dot2c_f32_bf16_e32 v240, v162, v106
	v_dot2c_f32_bf16_e32 v241, v170, v106
	v_dot2c_f32_bf16_e32 v240, v163, v107
	v_dot2c_f32_bf16_e32 v241, v171, v107
	v_readlane_b32 s5, v56, 0
	s_lshl_b32 s52, s5, 10
	s_add_u32 s56, s98, s52
	s_addc_u32 s57, s99, 0
	global_load_dwordx4 v[4:7], v62, s[56:57]
	v_readlane_b32 s6, v56, 32
	s_lshl_b32 s52, s6, 10
	s_add_u32 s56, s98, s52
	s_addc_u32 s57, s99, 0
	global_load_dwordx4 v[8:11], v62, s[56:57]
	s_waitcnt vmcnt(14)
	v_cvt_scalef32_pk_bf16_fp8 v156, v12, 1.0
	v_cvt_scalef32_pk_bf16_fp8 v157, v12, 1.0 op_sel:[1,0,0]
	v_cvt_scalef32_pk_bf16_fp8 v158, v13, 1.0
	v_cvt_scalef32_pk_bf16_fp8 v159, v13, 1.0 op_sel:[1,0,0]
	v_cvt_scalef32_pk_bf16_fp8 v160, v14, 1.0
	v_cvt_scalef32_pk_bf16_fp8 v161, v14, 1.0 op_sel:[1,0,0]
	v_cvt_scalef32_pk_bf16_fp8 v162, v15, 1.0
	v_cvt_scalef32_pk_bf16_fp8 v163, v15, 1.0 op_sel:[1,0,0]
	v_cvt_scalef32_pk_bf16_fp8 v164, v16, 1.0
	v_cvt_scalef32_pk_bf16_fp8 v165, v16, 1.0 op_sel:[1,0,0]
	v_cvt_scalef32_pk_bf16_fp8 v166, v17, 1.0
	v_cvt_scalef32_pk_bf16_fp8 v167, v17, 1.0 op_sel:[1,0,0]
	v_cvt_scalef32_pk_bf16_fp8 v168, v18, 1.0
	v_cvt_scalef32_pk_bf16_fp8 v169, v18, 1.0 op_sel:[1,0,0]
	v_cvt_scalef32_pk_bf16_fp8 v170, v19, 1.0
	v_cvt_scalef32_pk_bf16_fp8 v171, v19, 1.0 op_sel:[1,0,0]
	v_dot2_f32_bf16 v242, v156, v100, 0
	v_dot2_f32_bf16 v243, v164, v100, 0
	v_dot2c_f32_bf16_e32 v242, v157, v101
	v_dot2c_f32_bf16_e32 v243, v165, v101
	v_dot2c_f32_bf16_e32 v242, v158, v102
	v_dot2c_f32_bf16_e32 v243, v166, v102
	v_dot2c_f32_bf16_e32 v242, v159, v103
	v_dot2c_f32_bf16_e32 v243, v167, v103
	v_dot2c_f32_bf16_e32 v242, v160, v104
	v_dot2c_f32_bf16_e32 v243, v168, v104
	v_dot2c_f32_bf16_e32 v242, v161, v105
	v_dot2c_f32_bf16_e32 v243, v169, v105
	v_dot2c_f32_bf16_e32 v242, v162, v106
	v_dot2c_f32_bf16_e32 v243, v170, v106
	v_dot2c_f32_bf16_e32 v242, v163, v107
	v_dot2c_f32_bf16_e32 v243, v171, v107
	v_readlane_b32 s7, v56, 16
	s_lshl_b32 s52, s7, 10
	s_add_u32 s56, s98, s52
	s_addc_u32 s57, s99, 0
	global_load_dwordx4 v[12:15], v62, s[56:57]
	v_readlane_b32 s8, v56, 48
	s_lshl_b32 s52, s8, 10
	s_add_u32 s56, s98, s52
	s_addc_u32 s57, s99, 0
	global_load_dwordx4 v[16:19], v62, s[56:57]
	s_waitcnt vmcnt(14)
	v_cvt_scalef32_pk_bf16_fp8 v156, v20, 1.0
	v_cvt_scalef32_pk_bf16_fp8 v157, v20, 1.0 op_sel:[1,0,0]
	v_cvt_scalef32_pk_bf16_fp8 v158, v21, 1.0
	v_cvt_scalef32_pk_bf16_fp8 v159, v21, 1.0 op_sel:[1,0,0]
	v_cvt_scalef32_pk_bf16_fp8 v160, v22, 1.0
	v_cvt_scalef32_pk_bf16_fp8 v161, v22, 1.0 op_sel:[1,0,0]
	v_cvt_scalef32_pk_bf16_fp8 v162, v23, 1.0
	v_cvt_scalef32_pk_bf16_fp8 v163, v23, 1.0 op_sel:[1,0,0]
	v_cvt_scalef32_pk_bf16_fp8 v164, v24, 1.0
	v_cvt_scalef32_pk_bf16_fp8 v165, v24, 1.0 op_sel:[1,0,0]
	v_cvt_scalef32_pk_bf16_fp8 v166, v25, 1.0
	v_cvt_scalef32_pk_bf16_fp8 v167, v25, 1.0 op_sel:[1,0,0]
	v_cvt_scalef32_pk_bf16_fp8 v168, v26, 1.0
	v_cvt_scalef32_pk_bf16_fp8 v169, v26, 1.0 op_sel:[1,0,0]
	v_cvt_scalef32_pk_bf16_fp8 v170, v27, 1.0
	v_cvt_scalef32_pk_bf16_fp8 v171, v27, 1.0 op_sel:[1,0,0]
	v_dot2_f32_bf16 v244, v156, v100, 0
	v_dot2_f32_bf16 v245, v164, v100, 0
	v_dot2c_f32_bf16_e32 v244, v157, v101
	v_dot2c_f32_bf16_e32 v245, v165, v101
	v_dot2c_f32_bf16_e32 v244, v158, v102
	v_dot2c_f32_bf16_e32 v245, v166, v102
	v_dot2c_f32_bf16_e32 v244, v159, v103
	v_dot2c_f32_bf16_e32 v245, v167, v103
	v_dot2c_f32_bf16_e32 v244, v160, v104
	v_dot2c_f32_bf16_e32 v245, v168, v104
	v_dot2c_f32_bf16_e32 v244, v161, v105
	v_dot2c_f32_bf16_e32 v245, v169, v105
	v_dot2c_f32_bf16_e32 v244, v162, v106
	v_dot2c_f32_bf16_e32 v245, v170, v106
	v_dot2c_f32_bf16_e32 v244, v163, v107
	v_dot2c_f32_bf16_e32 v245, v171, v107
	v_readlane_b32 s9, v56, 8
	s_lshl_b32 s52, s9, 10
	s_add_u32 s56, s98, s52
	s_addc_u32 s57, s99, 0
	global_load_dwordx4 v[20:23], v62, s[56:57]
	v_readlane_b32 s11, v56, 40
	s_lshl_b32 s52, s11, 10
	s_add_u32 s56, s98, s52
	s_addc_u32 s57, s99, 0
	global_load_dwordx4 v[24:27], v62, s[56:57]
	s_waitcnt vmcnt(14)
	v_cvt_scalef32_pk_bf16_fp8 v156, v28, 1.0
	v_cvt_scalef32_pk_bf16_fp8 v157, v28, 1.0 op_sel:[1,0,0]
	v_cvt_scalef32_pk_bf16_fp8 v158, v29, 1.0
	v_cvt_scalef32_pk_bf16_fp8 v159, v29, 1.0 op_sel:[1,0,0]
	v_cvt_scalef32_pk_bf16_fp8 v160, v30, 1.0
	v_cvt_scalef32_pk_bf16_fp8 v161, v30, 1.0 op_sel:[1,0,0]
	v_cvt_scalef32_pk_bf16_fp8 v162, v31, 1.0
	v_cvt_scalef32_pk_bf16_fp8 v163, v31, 1.0 op_sel:[1,0,0]
	v_cvt_scalef32_pk_bf16_fp8 v164, v32, 1.0
	v_cvt_scalef32_pk_bf16_fp8 v165, v32, 1.0 op_sel:[1,0,0]
	v_cvt_scalef32_pk_bf16_fp8 v166, v33, 1.0
	v_cvt_scalef32_pk_bf16_fp8 v167, v33, 1.0 op_sel:[1,0,0]
	v_cvt_scalef32_pk_bf16_fp8 v168, v34, 1.0
	v_cvt_scalef32_pk_bf16_fp8 v169, v34, 1.0 op_sel:[1,0,0]
	v_cvt_scalef32_pk_bf16_fp8 v170, v35, 1.0
	v_cvt_scalef32_pk_bf16_fp8 v171, v35, 1.0 op_sel:[1,0,0]
	v_dot2_f32_bf16 v246, v156, v100, 0
	v_dot2_f32_bf16 v247, v164, v100, 0
	v_dot2c_f32_bf16_e32 v246, v157, v101
	v_dot2c_f32_bf16_e32 v247, v165, v101
	v_dot2c_f32_bf16_e32 v246, v158, v102
	v_dot2c_f32_bf16_e32 v247, v166, v102
	v_dot2c_f32_bf16_e32 v246, v159, v103
	v_dot2c_f32_bf16_e32 v247, v167, v103
	v_dot2c_f32_bf16_e32 v246, v160, v104
	v_dot2c_f32_bf16_e32 v247, v168, v104
	v_dot2c_f32_bf16_e32 v246, v161, v105
	v_dot2c_f32_bf16_e32 v247, v169, v105
	v_dot2c_f32_bf16_e32 v246, v162, v106
	v_dot2c_f32_bf16_e32 v247, v170, v106
	v_dot2c_f32_bf16_e32 v246, v163, v107
	v_dot2c_f32_bf16_e32 v247, v171, v107
	v_readlane_b32 s13, v56, 24
	s_lshl_b32 s52, s13, 10
	s_add_u32 s56, s98, s52
	s_addc_u32 s57, s99, 0
	global_load_dwordx4 v[28:31], v62, s[56:57]
	v_readlane_b32 s16, v56, 56
	s_lshl_b32 s52, s16, 10
	s_add_u32 s56, s98, s52
	s_addc_u32 s57, s99, 0
	global_load_dwordx4 v[32:35], v62, s[56:57]
	s_branch .Lex_d4
.Lex_d2:
	s_cmp_lg_u32 s15, 2
	s_cbranch_scc1 .Lex_d3
	s_waitcnt vmcnt(14)
	v_cvt_scalef32_pk_bf16_fp8 v156, v4, 1.0
	v_cvt_scalef32_pk_bf16_fp8 v157, v4, 1.0 op_sel:[1,0,0]
	v_cvt_scalef32_pk_bf16_fp8 v158, v5, 1.0
	v_cvt_scalef32_pk_bf16_fp8 v159, v5, 1.0 op_sel:[1,0,0]
	v_cvt_scalef32_pk_bf16_fp8 v160, v6, 1.0
	v_cvt_scalef32_pk_bf16_fp8 v161, v6, 1.0 op_sel:[1,0,0]
	v_cvt_scalef32_pk_bf16_fp8 v162, v7, 1.0
	v_cvt_scalef32_pk_bf16_fp8 v163, v7, 1.0 op_sel:[1,0,0]
	v_cvt_scalef32_pk_bf16_fp8 v164, v8, 1.0
	v_cvt_scalef32_pk_bf16_fp8 v165, v8, 1.0 op_sel:[1,0,0]
	v_cvt_scalef32_pk_bf16_fp8 v166, v9, 1.0
	v_cvt_scalef32_pk_bf16_fp8 v167, v9, 1.0 op_sel:[1,0,0]
	v_cvt_scalef32_pk_bf16_fp8 v168, v10, 1.0
	v_cvt_scalef32_pk_bf16_fp8 v169, v10, 1.0 op_sel:[1,0,0]
	v_cvt_scalef32_pk_bf16_fp8 v170, v11, 1.0
	v_cvt_scalef32_pk_bf16_fp8 v171, v11, 1.0 op_sel:[1,0,0]
	v_dot2_f32_bf16 v240, v156, v216, 0
	v_dot2_f32_bf16 v241, v164, v216, 0
	v_dot2c_f32_bf16_e32 v240, v157, v217
	v_dot2c_f32_bf16_e32 v241, v165, v217
	v_dot2c_f32_bf16_e32 v240, v158, v218
	v_dot2c_f32_bf16_e32 v241, v166, v218
	v_dot2c_f32_bf16_e32 v240, v159, v219
	v_dot2c_f32_bf16_e32 v241, v167, v219
	v_dot2c_f32_bf16_e32 v240, v160, v220
	v_dot2c_f32_bf16_e32 v241, v168, v220
	v_dot2c_f32_bf16_e32 v240, v161, v221
	v_dot2c_f32_bf16_e32 v241, v169, v221
	v_dot2c_f32_bf16_e32 v240, v162, v222
	v_dot2c_f32_bf16_e32 v241, v170, v222
	v_dot2c_f32_bf16_e32 v240, v163, v223
	v_dot2c_f32_bf16_e32 v241, v171, v223
	v_readlane_b32 s5, v56, 0
	s_lshl_b32 s52, s5, 10
	s_add_u32 s56, s98, s52
	s_addc_u32 s57, s99, 0
	global_load_dwordx4 v[4:7], v62, s[56:57]
	v_readlane_b32 s6, v56, 32
	s_lshl_b32 s52, s6, 10
	s_add_u32 s56, s98, s52
	s_addc_u32 s57, s99, 0
	global_load_dwordx4 v[8:11], v62, s[56:57]
	s_waitcnt vmcnt(14)
	v_cvt_scalef32_pk_bf16_fp8 v156, v12, 1.0
	v_cvt_scalef32_pk_bf16_fp8 v157, v12, 1.0 op_sel:[1,0,0]
	v_cvt_scalef32_pk_bf16_fp8 v158, v13, 1.0
	v_cvt_scalef32_pk_bf16_fp8 v159, v13, 1.0 op_sel:[1,0,0]
	v_cvt_scalef32_pk_bf16_fp8 v160, v14, 1.0
	v_cvt_scalef32_pk_bf16_fp8 v161, v14, 1.0 op_sel:[1,0,0]
	v_cvt_scalef32_pk_bf16_fp8 v162, v15, 1.0
	v_cvt_scalef32_pk_bf16_fp8 v163, v15, 1.0 op_sel:[1,0,0]
	v_cvt_scalef32_pk_bf16_fp8 v164, v16, 1.0
	v_cvt_scalef32_pk_bf16_fp8 v165, v16, 1.0 op_sel:[1,0,0]
	v_cvt_scalef32_pk_bf16_fp8 v166, v17, 1.0
	v_cvt_scalef32_pk_bf16_fp8 v167, v17, 1.0 op_sel:[1,0,0]
	v_cvt_scalef32_pk_bf16_fp8 v168, v18, 1.0
	v_cvt_scalef32_pk_bf16_fp8 v169, v18, 1.0 op_sel:[1,0,0]
	v_cvt_scalef32_pk_bf16_fp8 v170, v19, 1.0
	v_cvt_scalef32_pk_bf16_fp8 v171, v19, 1.0 op_sel:[1,0,0]
	v_dot2_f32_bf16 v242, v156, v216, 0
	v_dot2_f32_bf16 v243, v164, v216, 0
	v_dot2c_f32_bf16_e32 v242, v157, v217
	v_dot2c_f32_bf16_e32 v243, v165, v217
	v_dot2c_f32_bf16_e32 v242, v158, v218
	v_dot2c_f32_bf16_e32 v243, v166, v218
	v_dot2c_f32_bf16_e32 v242, v159, v219
	v_dot2c_f32_bf16_e32 v243, v167, v219
	v_dot2c_f32_bf16_e32 v242, v160, v220
	v_dot2c_f32_bf16_e32 v243, v168, v220
	v_dot2c_f32_bf16_e32 v242, v161, v221
	v_dot2c_f32_bf16_e32 v243, v169, v221
	v_dot2c_f32_bf16_e32 v242, v162, v222
	v_dot2c_f32_bf16_e32 v243, v170, v222
	v_dot2c_f32_bf16_e32 v242, v163, v223
	v_dot2c_f32_bf16_e32 v243, v171, v223
	v_readlane_b32 s7, v56, 16
	s_lshl_b32 s52, s7, 10
	s_add_u32 s56, s98, s52
	s_addc_u32 s57, s99, 0
	global_load_dwordx4 v[12:15], v62, s[56:57]
	v_readlane_b32 s8, v56, 48
	s_lshl_b32 s52, s8, 10
	s_add_u32 s56, s98, s52
	s_addc_u32 s57, s99, 0
	global_load_dwordx4 v[16:19], v62, s[56:57]
	s_waitcnt vmcnt(14)
	v_cvt_scalef32_pk_bf16_fp8 v156, v20, 1.0
	v_cvt_scalef32_pk_bf16_fp8 v157, v20, 1.0 op_sel:[1,0,0]
	v_cvt_scalef32_pk_bf16_fp8 v158, v21, 1.0
	v_cvt_scalef32_pk_bf16_fp8 v159, v21, 1.0 op_sel:[1,0,0]
	v_cvt_scalef32_pk_bf16_fp8 v160, v22, 1.0
	v_cvt_scalef32_pk_bf16_fp8 v161, v22, 1.0 op_sel:[1,0,0]
	v_cvt_scalef32_pk_bf16_fp8 v162, v23, 1.0
	v_cvt_scalef32_pk_bf16_fp8 v163, v23, 1.0 op_sel:[1,0,0]
	v_cvt_scalef32_pk_bf16_fp8 v164, v24, 1.0
	v_cvt_scalef32_pk_bf16_fp8 v165, v24, 1.0 op_sel:[1,0,0]
	v_cvt_scalef32_pk_bf16_fp8 v166, v25, 1.0
	v_cvt_scalef32_pk_bf16_fp8 v167, v25, 1.0 op_sel:[1,0,0]
	v_cvt_scalef32_pk_bf16_fp8 v168, v26, 1.0
	v_cvt_scalef32_pk_bf16_fp8 v169, v26, 1.0 op_sel:[1,0,0]
	v_cvt_scalef32_pk_bf16_fp8 v170, v27, 1.0
	v_cvt_scalef32_pk_bf16_fp8 v171, v27, 1.0 op_sel:[1,0,0]
	v_dot2_f32_bf16 v244, v156, v216, 0
	v_dot2_f32_bf16 v245, v164, v216, 0
	v_dot2c_f32_bf16_e32 v244, v157, v217
	v_dot2c_f32_bf16_e32 v245, v165, v217
	v_dot2c_f32_bf16_e32 v244, v158, v218
	v_dot2c_f32_bf16_e32 v245, v166, v218
	v_dot2c_f32_bf16_e32 v244, v159, v219
	v_dot2c_f32_bf16_e32 v245, v167, v219
	v_dot2c_f32_bf16_e32 v244, v160, v220
	v_dot2c_f32_bf16_e32 v245, v168, v220
	v_dot2c_f32_bf16_e32 v244, v161, v221
	v_dot2c_f32_bf16_e32 v245, v169, v221
	v_dot2c_f32_bf16_e32 v244, v162, v222
	v_dot2c_f32_bf16_e32 v245, v170, v222
	v_dot2c_f32_bf16_e32 v244, v163, v223
	v_dot2c_f32_bf16_e32 v245, v171, v223
	v_readlane_b32 s9, v56, 8
	s_lshl_b32 s52, s9, 10
	s_add_u32 s56, s98, s52
	s_addc_u32 s57, s99, 0
	global_load_dwordx4 v[20:23], v62, s[56:57]
	v_readlane_b32 s11, v56, 40
	s_lshl_b32 s52, s11, 10
	s_add_u32 s56, s98, s52
	s_addc_u32 s57, s99, 0
	global_load_dwordx4 v[24:27], v62, s[56:57]
	s_waitcnt vmcnt(14)
	v_cvt_scalef32_pk_bf16_fp8 v156, v28, 1.0
	v_cvt_scalef32_pk_bf16_fp8 v157, v28, 1.0 op_sel:[1,0,0]
	v_cvt_scalef32_pk_bf16_fp8 v158, v29, 1.0
	v_cvt_scalef32_pk_bf16_fp8 v159, v29, 1.0 op_sel:[1,0,0]
	v_cvt_scalef32_pk_bf16_fp8 v160, v30, 1.0
	v_cvt_scalef32_pk_bf16_fp8 v161, v30, 1.0 op_sel:[1,0,0]
	v_cvt_scalef32_pk_bf16_fp8 v162, v31, 1.0
	v_cvt_scalef32_pk_bf16_fp8 v163, v31, 1.0 op_sel:[1,0,0]
	v_cvt_scalef32_pk_bf16_fp8 v164, v32, 1.0
	v_cvt_scalef32_pk_bf16_fp8 v165, v32, 1.0 op_sel:[1,0,0]
	v_cvt_scalef32_pk_bf16_fp8 v166, v33, 1.0
	v_cvt_scalef32_pk_bf16_fp8 v167, v33, 1.0 op_sel:[1,0,0]
	v_cvt_scalef32_pk_bf16_fp8 v168, v34, 1.0
	v_cvt_scalef32_pk_bf16_fp8 v169, v34, 1.0 op_sel:[1,0,0]
	v_cvt_scalef32_pk_bf16_fp8 v170, v35, 1.0
	v_cvt_scalef32_pk_bf16_fp8 v171, v35, 1.0 op_sel:[1,0,0]
	v_dot2_f32_bf16 v246, v156, v216, 0
	v_dot2_f32_bf16 v247, v164, v216, 0
	v_dot2c_f32_bf16_e32 v246, v157, v217
	v_dot2c_f32_bf16_e32 v247, v165, v217
	v_dot2c_f32_bf16_e32 v246, v158, v218
	v_dot2c_f32_bf16_e32 v247, v166, v218
	v_dot2c_f32_bf16_e32 v246, v159, v219
	v_dot2c_f32_bf16_e32 v247, v167, v219
	v_dot2c_f32_bf16_e32 v246, v160, v220
	v_dot2c_f32_bf16_e32 v247, v168, v220
	v_dot2c_f32_bf16_e32 v246, v161, v221
	v_dot2c_f32_bf16_e32 v247, v169, v221
	v_dot2c_f32_bf16_e32 v246, v162, v222
	v_dot2c_f32_bf16_e32 v247, v170, v222
	v_dot2c_f32_bf16_e32 v246, v163, v223
	v_dot2c_f32_bf16_e32 v247, v171, v223
	v_readlane_b32 s13, v56, 24
	s_lshl_b32 s52, s13, 10
	s_add_u32 s56, s98, s52
	s_addc_u32 s57, s99, 0
	global_load_dwordx4 v[28:31], v62, s[56:57]
	v_readlane_b32 s16, v56, 56
	s_lshl_b32 s52, s16, 10
	s_add_u32 s56, s98, s52
	s_addc_u32 s57, s99, 0
	global_load_dwordx4 v[32:35], v62, s[56:57]
	s_branch .Lex_d4
.Lex_d3:
	s_waitcnt vmcnt(14)
	v_cvt_scalef32_pk_bf16_fp8 v156, v4, 1.0
	v_cvt_scalef32_pk_bf16_fp8 v157, v4, 1.0 op_sel:[1,0,0]
	v_cvt_scalef32_pk_bf16_fp8 v158, v5, 1.0
	v_cvt_scalef32_pk_bf16_fp8 v159, v5, 1.0 op_sel:[1,0,0]
	v_cvt_scalef32_pk_bf16_fp8 v160, v6, 1.0
	v_cvt_scalef32_pk_bf16_fp8 v161, v6, 1.0 op_sel:[1,0,0]
	v_cvt_scalef32_pk_bf16_fp8 v162, v7, 1.0
	v_cvt_scalef32_pk_bf16_fp8 v163, v7, 1.0 op_sel:[1,0,0]
	v_cvt_scalef32_pk_bf16_fp8 v164, v8, 1.0
	v_cvt_scalef32_pk_bf16_fp8 v165, v8, 1.0 op_sel:[1,0,0]
	v_cvt_scalef32_pk_bf16_fp8 v166, v9, 1.0
	v_cvt_scalef32_pk_bf16_fp8 v167, v9, 1.0 op_sel:[1,0,0]
	v_cvt_scalef32_pk_bf16_fp8 v168, v10, 1.0
	v_cvt_scalef32_pk_bf16_fp8 v169, v10, 1.0 op_sel:[1,0,0]
	v_cvt_scalef32_pk_bf16_fp8 v170, v11, 1.0
	v_cvt_scalef32_pk_bf16_fp8 v171, v11, 1.0 op_sel:[1,0,0]
	v_dot2_f32_bf16 v240, v156, v224, 0
	v_dot2_f32_bf16 v241, v164, v224, 0
	v_dot2c_f32_bf16_e32 v240, v157, v225
	v_dot2c_f32_bf16_e32 v241, v165, v225
	v_dot2c_f32_bf16_e32 v240, v158, v226
	v_dot2c_f32_bf16_e32 v241, v166, v226
	v_dot2c_f32_bf16_e32 v240, v159, v227
	v_dot2c_f32_bf16_e32 v241, v167, v227
	v_dot2c_f32_bf16_e32 v240, v160, v228
	v_dot2c_f32_bf16_e32 v241, v168, v228
	v_dot2c_f32_bf16_e32 v240, v161, v229
	v_dot2c_f32_bf16_e32 v241, v169, v229
	v_dot2c_f32_bf16_e32 v240, v162, v230
	v_dot2c_f32_bf16_e32 v241, v170, v230
	v_dot2c_f32_bf16_e32 v240, v163, v231
	v_dot2c_f32_bf16_e32 v241, v171, v231
	v_readlane_b32 s5, v56, 0
	s_lshl_b32 s52, s5, 10
	s_add_u32 s56, s98, s52
	s_addc_u32 s57, s99, 0
	global_load_dwordx4 v[4:7], v62, s[56:57]
	v_readlane_b32 s6, v56, 32
	s_lshl_b32 s52, s6, 10
	s_add_u32 s56, s98, s52
	s_addc_u32 s57, s99, 0
	global_load_dwordx4 v[8:11], v62, s[56:57]
	s_waitcnt vmcnt(14)
	v_cvt_scalef32_pk_bf16_fp8 v156, v12, 1.0
	v_cvt_scalef32_pk_bf16_fp8 v157, v12, 1.0 op_sel:[1,0,0]
	v_cvt_scalef32_pk_bf16_fp8 v158, v13, 1.0
	v_cvt_scalef32_pk_bf16_fp8 v159, v13, 1.0 op_sel:[1,0,0]
	v_cvt_scalef32_pk_bf16_fp8 v160, v14, 1.0
	v_cvt_scalef32_pk_bf16_fp8 v161, v14, 1.0 op_sel:[1,0,0]
	v_cvt_scalef32_pk_bf16_fp8 v162, v15, 1.0
	v_cvt_scalef32_pk_bf16_fp8 v163, v15, 1.0 op_sel:[1,0,0]
	v_cvt_scalef32_pk_bf16_fp8 v164, v16, 1.0
	v_cvt_scalef32_pk_bf16_fp8 v165, v16, 1.0 op_sel:[1,0,0]
	v_cvt_scalef32_pk_bf16_fp8 v166, v17, 1.0
	v_cvt_scalef32_pk_bf16_fp8 v167, v17, 1.0 op_sel:[1,0,0]
	v_cvt_scalef32_pk_bf16_fp8 v168, v18, 1.0
	v_cvt_scalef32_pk_bf16_fp8 v169, v18, 1.0 op_sel:[1,0,0]
	v_cvt_scalef32_pk_bf16_fp8 v170, v19, 1.0
	v_cvt_scalef32_pk_bf16_fp8 v171, v19, 1.0 op_sel:[1,0,0]
	v_dot2_f32_bf16 v242, v156, v224, 0
	v_dot2_f32_bf16 v243, v164, v224, 0
	v_dot2c_f32_bf16_e32 v242, v157, v225
	v_dot2c_f32_bf16_e32 v243, v165, v225
	v_dot2c_f32_bf16_e32 v242, v158, v226
	v_dot2c_f32_bf16_e32 v243, v166, v226
	v_dot2c_f32_bf16_e32 v242, v159, v227
	v_dot2c_f32_bf16_e32 v243, v167, v227
	v_dot2c_f32_bf16_e32 v242, v160, v228
	v_dot2c_f32_bf16_e32 v243, v168, v228
	v_dot2c_f32_bf16_e32 v242, v161, v229
	v_dot2c_f32_bf16_e32 v243, v169, v229
	v_dot2c_f32_bf16_e32 v242, v162, v230
	v_dot2c_f32_bf16_e32 v243, v170, v230
	v_dot2c_f32_bf16_e32 v242, v163, v231
	v_dot2c_f32_bf16_e32 v243, v171, v231
	v_readlane_b32 s7, v56, 16
	s_lshl_b32 s52, s7, 10
	s_add_u32 s56, s98, s52
	s_addc_u32 s57, s99, 0
	global_load_dwordx4 v[12:15], v62, s[56:57]
	v_readlane_b32 s8, v56, 48
	s_lshl_b32 s52, s8, 10
	s_add_u32 s56, s98, s52
	s_addc_u32 s57, s99, 0
	global_load_dwordx4 v[16:19], v62, s[56:57]
	s_waitcnt vmcnt(14)
	v_cvt_scalef32_pk_bf16_fp8 v156, v20, 1.0
	v_cvt_scalef32_pk_bf16_fp8 v157, v20, 1.0 op_sel:[1,0,0]
	v_cvt_scalef32_pk_bf16_fp8 v158, v21, 1.0
	v_cvt_scalef32_pk_bf16_fp8 v159, v21, 1.0 op_sel:[1,0,0]
	v_cvt_scalef32_pk_bf16_fp8 v160, v22, 1.0
	v_cvt_scalef32_pk_bf16_fp8 v161, v22, 1.0 op_sel:[1,0,0]
	v_cvt_scalef32_pk_bf16_fp8 v162, v23, 1.0
	v_cvt_scalef32_pk_bf16_fp8 v163, v23, 1.0 op_sel:[1,0,0]
	v_cvt_scalef32_pk_bf16_fp8 v164, v24, 1.0
	v_cvt_scalef32_pk_bf16_fp8 v165, v24, 1.0 op_sel:[1,0,0]
	v_cvt_scalef32_pk_bf16_fp8 v166, v25, 1.0
	v_cvt_scalef32_pk_bf16_fp8 v167, v25, 1.0 op_sel:[1,0,0]
	v_cvt_scalef32_pk_bf16_fp8 v168, v26, 1.0
	v_cvt_scalef32_pk_bf16_fp8 v169, v26, 1.0 op_sel:[1,0,0]
	v_cvt_scalef32_pk_bf16_fp8 v170, v27, 1.0
	v_cvt_scalef32_pk_bf16_fp8 v171, v27, 1.0 op_sel:[1,0,0]
	v_dot2_f32_bf16 v244, v156, v224, 0
	v_dot2_f32_bf16 v245, v164, v224, 0
	v_dot2c_f32_bf16_e32 v244, v157, v225
	v_dot2c_f32_bf16_e32 v245, v165, v225
	v_dot2c_f32_bf16_e32 v244, v158, v226
	v_dot2c_f32_bf16_e32 v245, v166, v226
	v_dot2c_f32_bf16_e32 v244, v159, v227
	v_dot2c_f32_bf16_e32 v245, v167, v227
	v_dot2c_f32_bf16_e32 v244, v160, v228
	v_dot2c_f32_bf16_e32 v245, v168, v228
	v_dot2c_f32_bf16_e32 v244, v161, v229
	v_dot2c_f32_bf16_e32 v245, v169, v229
	v_dot2c_f32_bf16_e32 v244, v162, v230
	v_dot2c_f32_bf16_e32 v245, v170, v230
	v_dot2c_f32_bf16_e32 v244, v163, v231
	v_dot2c_f32_bf16_e32 v245, v171, v231
	v_readlane_b32 s9, v56, 8
	s_lshl_b32 s52, s9, 10
	s_add_u32 s56, s98, s52
	s_addc_u32 s57, s99, 0
	global_load_dwordx4 v[20:23], v62, s[56:57]
	v_readlane_b32 s11, v56, 40
	s_lshl_b32 s52, s11, 10
	s_add_u32 s56, s98, s52
	s_addc_u32 s57, s99, 0
	global_load_dwordx4 v[24:27], v62, s[56:57]
	s_waitcnt vmcnt(14)
	v_cvt_scalef32_pk_bf16_fp8 v156, v28, 1.0
	v_cvt_scalef32_pk_bf16_fp8 v157, v28, 1.0 op_sel:[1,0,0]
	v_cvt_scalef32_pk_bf16_fp8 v158, v29, 1.0
	v_cvt_scalef32_pk_bf16_fp8 v159, v29, 1.0 op_sel:[1,0,0]
	v_cvt_scalef32_pk_bf16_fp8 v160, v30, 1.0
	v_cvt_scalef32_pk_bf16_fp8 v161, v30, 1.0 op_sel:[1,0,0]
	v_cvt_scalef32_pk_bf16_fp8 v162, v31, 1.0
	v_cvt_scalef32_pk_bf16_fp8 v163, v31, 1.0 op_sel:[1,0,0]
	v_cvt_scalef32_pk_bf16_fp8 v164, v32, 1.0
	v_cvt_scalef32_pk_bf16_fp8 v165, v32, 1.0 op_sel:[1,0,0]
	v_cvt_scalef32_pk_bf16_fp8 v166, v33, 1.0
	v_cvt_scalef32_pk_bf16_fp8 v167, v33, 1.0 op_sel:[1,0,0]
	v_cvt_scalef32_pk_bf16_fp8 v168, v34, 1.0
	v_cvt_scalef32_pk_bf16_fp8 v169, v34, 1.0 op_sel:[1,0,0]
	v_cvt_scalef32_pk_bf16_fp8 v170, v35, 1.0
	v_cvt_scalef32_pk_bf16_fp8 v171, v35, 1.0 op_sel:[1,0,0]
	v_dot2_f32_bf16 v246, v156, v224, 0
	v_dot2_f32_bf16 v247, v164, v224, 0
	v_dot2c_f32_bf16_e32 v246, v157, v225
	v_dot2c_f32_bf16_e32 v247, v165, v225
	v_dot2c_f32_bf16_e32 v246, v158, v226
	v_dot2c_f32_bf16_e32 v247, v166, v226
	v_dot2c_f32_bf16_e32 v246, v159, v227
	v_dot2c_f32_bf16_e32 v247, v167, v227
	v_dot2c_f32_bf16_e32 v246, v160, v228
	v_dot2c_f32_bf16_e32 v247, v168, v228
	v_dot2c_f32_bf16_e32 v246, v161, v229
	v_dot2c_f32_bf16_e32 v247, v169, v229
	v_dot2c_f32_bf16_e32 v246, v162, v230
	v_dot2c_f32_bf16_e32 v247, v170, v230
	v_dot2c_f32_bf16_e32 v246, v163, v231
	v_dot2c_f32_bf16_e32 v247, v171, v231
	v_readlane_b32 s13, v56, 24
	s_lshl_b32 s52, s13, 10
	s_add_u32 s56, s98, s52
	s_addc_u32 s57, s99, 0
	global_load_dwordx4 v[28:31], v62, s[56:57]
	v_readlane_b32 s16, v56, 56
	s_lshl_b32 s52, s16, 10
	s_add_u32 s56, s98, s52
	s_addc_u32 s57, s99, 0
	global_load_dwordx4 v[32:35], v62, s[56:57]

.Lex_d9:
	v_mov_b32_e32 v52, v56
	v_mov_b32_e32 v53, v57
	v_mov_b32_e32 v54, v58
	v_mov_b32_e32 v55, v59
	s_lshr_b32 s15, s14, 4
	s_add_i32 s4, s4, 1
	s_cmp_lt_u32 s4, 64
	s_cbranch_scc1 .Lex_grp
	s_waitcnt vmcnt(0)
	s_lshl_b32 s10, s12, 2
	v_add_u32_e32 v64, s10, v79
	v_ashrrev_i32_e32 v65, 31, v64
	v_lshl_add_u64 v[64:65], s[28:29], 0, v[64:65]
	v_lshlrev_b64 v[0:1], 11, v[64:65]
	v_lshl_add_u64 v[0:1], v[80:81], 0, v[0:1]
	v_mov_b32_e32 v44, v100
	v_mov_b32_e32 v45, v101
	v_mov_b32_e32 v46, v102
	v_mov_b32_e32 v47, v103
	v_mov_b32_e32 v48, v104
	v_mov_b32_e32 v49, v105
	v_mov_b32_e32 v50, v106
	v_mov_b32_e32 v51, v107
	v_mov_b32_e32 v52, v92
	v_mov_b32_e32 v53, v93
	v_mov_b32_e32 v54, v94
	v_mov_b32_e32 v55, v95
	v_mov_b32_e32 v56, v96
	v_mov_b32_e32 v57, v97
	v_mov_b32_e32 v58, v98
	v_mov_b32_e32 v59, v99
	v_lshlrev_b32_e32 v96, 16, v52
	v_and_b32_e32 v97, 0xffff0000, v52
	v_lshlrev_b32_e32 v92, 16, v56
	v_and_b32_e32 v93, 0xffff0000, v56
	v_lshlrev_b32_e32 v98, 16, v53
	v_and_b32_e32 v99, 0xffff0000, v53
	v_lshlrev_b32_e32 v94, 16, v57
	v_and_b32_e32 v95, 0xffff0000, v57
	v_lshlrev_b32_e32 v100, 16, v54
	v_and_b32_e32 v101, 0xffff0000, v54
	v_lshlrev_b32_e32 v104, 16, v58
	v_and_b32_e32 v105, 0xffff0000, v58
	v_lshlrev_b32_e32 v102, 16, v55
	v_and_b32_e32 v103, 0xffff0000, v55
	v_lshlrev_b32_e32 v106, 16, v59
	v_and_b32_e32 v107, 0xffff0000, v59
	v_mov_b32_e32 v134, v108
	v_mov_b32_e32 v135, v109
	v_mov_b32_e32 v150, v110
	v_mov_b32_e32 v151, v111
	v_mov_b32_e32 v148, v112
	v_mov_b32_e32 v149, v113
	v_mov_b32_e32 v146, v114
	v_mov_b32_e32 v147, v115
	v_mov_b32_e32 v144, v116
	v_mov_b32_e32 v145, v117
	v_mov_b32_e32 v142, v118
	v_mov_b32_e32 v143, v119
	v_mov_b32_e32 v152, v120
	v_mov_b32_e32 v153, v121
	v_mov_b32_e32 v154, v122
	v_mov_b32_e32 v155, v123
	v_lshlrev_b64 v[0:1], 10, v[64:65]
	global_load_dwordx4 v[4:7], v[88:89], off
	global_load_dwordx4 v[8:11], v[90:91], off
	v_pk_fma_f32 v[16:17], v[96:97], s[26:27], v[134:135] op_sel_hi:[1,0,1]
	v_pk_fma_f32 v[18:19], v[98:99], s[26:27], v[150:151] op_sel_hi:[1,0,1]
	v_add_f32_e32 v2, 0, v16
	v_add_f32_e32 v2, v17, v2
	v_add_f32_e32 v2, v18, v2
	v_add_f32_e32 v2, v19, v2
	v_pk_fma_f32 v[20:21], v[100:101], s[26:27], v[148:149] op_sel_hi:[1,0,1]
	v_pk_fma_f32 v[22:23], v[102:103], s[26:27], v[146:147] op_sel_hi:[1,0,1]
	v_add_f32_e32 v2, v20, v2
	v_add_f32_e32 v2, v21, v2
	v_add_f32_e32 v2, v22, v2
	v_add_f32_e32 v2, v23, v2
	v_pk_fma_f32 v[24:25], v[92:93], s[26:27], v[144:145] op_sel_hi:[1,0,1]
	v_pk_fma_f32 v[26:27], v[94:95], s[26:27], v[142:143] op_sel_hi:[1,0,1]
	v_add_f32_e32 v2, v24, v2
	v_add_f32_e32 v2, v25, v2
	v_add_f32_e32 v2, v26, v2
	v_pk_fma_f32 v[12:13], v[104:105], s[26:27], v[152:153] op_sel_hi:[1,0,1]
	v_add_f32_e32 v2, v27, v2
	v_add_f32_e32 v2, v12, v2
	v_pk_fma_f32 v[14:15], v[106:107], s[26:27], v[154:155] op_sel_hi:[1,0,1]
	v_add_f32_e32 v2, v13, v2
	v_add_f32_e32 v2, v14, v2
	v_add_f32_e32 v2, v15, v2
	v_mov_b32_e32 v28, 0
	v_lshl_add_u64 v[0:1], v[0:1], 2, v[86:87]
	v_add_f32_dpp v2, v2, v2 quad_perm:[1,0,3,2] row_mask:0xf bank_mask:0xf bound_ctrl:1
	s_nop 0
	s_nop 0
	v_add_f32_dpp v2, v2, v2 quad_perm:[2,3,0,1] row_mask:0xf bank_mask:0xf bound_ctrl:1
	s_nop 0
	s_nop 0
	v_add_f32_dpp v2, v2, v2 row_half_mirror row_mask:0xf bank_mask:0xf bound_ctrl:1
	s_nop 1
	v_add_f32_dpp v2, v2, v2 row_mirror row_mask:0xf bank_mask:0xf bound_ctrl:1
	s_nop 1
	v_mov_b32_dpp v28, v2 row_bcast:15 row_mask:0xa bank_mask:0xf
	v_add_f32_e32 v2, v2, v28
	v_mov_b32_e32 v28, 0
	s_nop 1
	v_mov_b32_dpp v28, v2 row_bcast:31 row_mask:0xc bank_mask:0xf
	v_add_f32_e32 v2, v2, v28
	s_nop 0
	v_readlane_b32 s34, v2, 63
	s_nop 1
	v_mul_f32_e32 v2, s34, v180
	v_pk_add_f32 v[16:17], v[16:17], v[2:3] op_sel_hi:[1,0] neg_lo:[0,1] neg_hi:[0,1]
	v_pk_add_f32 v[18:19], v[18:19], v[2:3] op_sel_hi:[1,0] neg_lo:[0,1] neg_hi:[0,1]
	v_pk_mul_f32 v[28:29], v[16:17], v[16:17]
	v_pk_mul_f32 v[30:31], v[18:19], v[18:19]
	v_pk_add_f32 v[20:21], v[20:21], v[2:3] op_sel_hi:[1,0] neg_lo:[0,1] neg_hi:[0,1]
	v_pk_add_f32 v[22:23], v[22:23], v[2:3] op_sel_hi:[1,0] neg_lo:[0,1] neg_hi:[0,1]
	v_pk_add_f32 v[24:25], v[24:25], v[2:3] op_sel_hi:[1,0] neg_lo:[0,1] neg_hi:[0,1]
	v_pk_add_f32 v[26:27], v[26:27], v[2:3] op_sel_hi:[1,0] neg_lo:[0,1] neg_hi:[0,1]
	v_pk_add_f32 v[12:13], v[12:13], v[2:3] op_sel_hi:[1,0] neg_lo:[0,1] neg_hi:[0,1]
	v_pk_add_f32 v[14:15], v[14:15], v[2:3] op_sel_hi:[1,0] neg_lo:[0,1] neg_hi:[0,1]
	v_add_f32_e32 v2, v28, v29
	v_add_f32_e32 v2, v30, v2
	v_pk_mul_f32 v[32:33], v[20:21], v[20:21]
	v_add_f32_e32 v2, v31, v2
	v_add_f32_e32 v2, v32, v2
	v_pk_mul_f32 v[34:35], v[22:23], v[22:23]
	v_add_f32_e32 v2, v33, v2
	v_add_f32_e32 v2, v34, v2
	v_pk_mul_f32 v[36:37], v[24:25], v[24:25]
	v_add_f32_e32 v2, v35, v2
	v_add_f32_e32 v2, v36, v2
	v_pk_mul_f32 v[38:39], v[26:27], v[26:27]
	v_add_f32_e32 v2, v37, v2
	v_add_f32_e32 v2, v38, v2
	v_pk_mul_f32 v[40:41], v[12:13], v[12:13]
	v_add_f32_e32 v2, v39, v2
	v_add_f32_e32 v2, v40, v2
	v_pk_mul_f32 v[42:43], v[14:15], v[14:15]
	v_add_f32_e32 v2, v41, v2
	v_add_f32_e32 v2, v42, v2
	v_add_f32_e32 v2, v43, v2
	v_mov_b32_e32 v28, 0
	s_nop 0
	v_add_f32_dpp v2, v2, v2 quad_perm:[1,0,3,2] row_mask:0xf bank_mask:0xf bound_ctrl:1
	s_nop 1
	v_add_f32_dpp v2, v2, v2 quad_perm:[2,3,0,1] row_mask:0xf bank_mask:0xf bound_ctrl:1
	s_nop 1
	v_add_f32_dpp v2, v2, v2 row_half_mirror row_mask:0xf bank_mask:0xf bound_ctrl:1
	s_nop 1
	v_add_f32_dpp v2, v2, v2 row_mirror row_mask:0xf bank_mask:0xf bound_ctrl:1
	s_nop 1
	v_mov_b32_dpp v28, v2 row_bcast:15 row_mask:0xa bank_mask:0xf
	v_add_f32_e32 v2, v2, v28
	v_mov_b32_e32 v28, 0
	s_nop 1
	v_mov_b32_dpp v28, v2 row_bcast:31 row_mask:0xc bank_mask:0xf
	v_add_f32_e32 v2, v2, v28
	s_nop 0
	v_readlane_b32 s34, v2, 63
	s_nop 1
	v_fma_f32 v2, s34, v180, v177
	v_mul_f32_e32 v28, 0x4b800000, v2
	v_cmp_gt_f32_e32 vcc, s49, v2
	s_nop 1
	v_cndmask_b32_e32 v2, v2, v28, vcc
	v_rsq_f32_e32 v2, v2
	s_nop 0
	v_mul_f32_e32 v28, 0x45800000, v2
	v_cndmask_b32_e32 v2, v2, v28, vcc
	v_pk_mul_f32 v[16:17], v[16:17], v[2:3] op_sel_hi:[1,0]
	v_pk_mul_f32 v[18:19], v[18:19], v[2:3] op_sel_hi:[1,0]
	s_waitcnt vmcnt(0)
	v_pk_fma_f32 v[4:5], v[4:5], v[16:17], v[8:9]
	v_pk_fma_f32 v[6:7], v[6:7], v[18:19], v[10:11]
	global_store_dwordx4 v[0:1], v[4:7], off
	global_load_dwordx4 v[4:7], v[88:89], off offset:16
	s_nop 0
	global_load_dwordx4 v[8:11], v[90:91], off offset:16
	v_pk_mul_f32 v[16:17], v[22:23], v[2:3] op_sel_hi:[1,0]
	v_pk_mul_f32 v[18:19], v[20:21], v[2:3] op_sel_hi:[1,0]
	v_pk_mul_f32 v[14:15], v[14:15], v[2:3] op_sel_hi:[1,0]
	v_pk_mul_f32 v[12:13], v[12:13], v[2:3] op_sel_hi:[1,0]
	s_waitcnt vmcnt(0)
	v_pk_fma_f32 v[4:5], v[4:5], v[18:19], v[8:9]
	v_pk_fma_f32 v[6:7], v[6:7], v[16:17], v[10:11]
	global_store_dwordx4 v[0:1], v[4:7], off offset:16
	global_load_dwordx4 v[4:7], v[88:89], off offset:32
	s_nop 0
	global_load_dwordx4 v[8:11], v[90:91], off offset:32
	v_pk_mul_f32 v[16:17], v[26:27], v[2:3] op_sel_hi:[1,0]
	v_pk_mul_f32 v[18:19], v[24:25], v[2:3] op_sel_hi:[1,0]
	s_waitcnt vmcnt(0)
	v_pk_fma_f32 v[6:7], v[6:7], v[16:17], v[10:11]
	v_pk_fma_f32 v[4:5], v[4:5], v[18:19], v[8:9]
	global_store_dwordx4 v[0:1], v[4:7], off offset:32
	global_load_dwordx4 v[4:7], v[88:89], off offset:48
	s_nop 0
	global_load_dwordx4 v[8:11], v[90:91], off offset:48
	s_waitcnt vmcnt(0)
	v_pk_fma_f32 v[4:5], v[12:13], v[4:5], v[8:9]
	v_pk_fma_f32 v[6:7], v[14:15], v[6:7], v[10:11]
	global_store_dwordx4 v[0:1], v[4:7], off offset:48
	s_lshl_b32 s10, s12, 2
	s_add_i32 s10, s10, 1
	v_add_u32_e32 v64, s10, v79
	v_ashrrev_i32_e32 v65, 31, v64
	v_lshl_add_u64 v[64:65], s[28:29], 0, v[64:65]
	v_lshlrev_b64 v[0:1], 11, v[64:65]
	v_lshl_add_u64 v[0:1], v[80:81], 0, v[0:1]
	v_mov_b32_e32 v52, v44
	v_mov_b32_e32 v53, v45
	v_mov_b32_e32 v54, v46
	v_mov_b32_e32 v55, v47
	v_mov_b32_e32 v56, v48
	v_mov_b32_e32 v57, v49
	v_mov_b32_e32 v58, v50
	v_mov_b32_e32 v59, v51
	v_lshlrev_b32_e32 v96, 16, v52
	v_and_b32_e32 v97, 0xffff0000, v52
	v_lshlrev_b32_e32 v92, 16, v56
	v_and_b32_e32 v93, 0xffff0000, v56
	v_lshlrev_b32_e32 v98, 16, v53
	v_and_b32_e32 v99, 0xffff0000, v53
	v_lshlrev_b32_e32 v94, 16, v57
	v_and_b32_e32 v95, 0xffff0000, v57
	v_lshlrev_b32_e32 v100, 16, v54
	v_and_b32_e32 v101, 0xffff0000, v54
	v_lshlrev_b32_e32 v104, 16, v58
	v_and_b32_e32 v105, 0xffff0000, v58
	v_lshlrev_b32_e32 v102, 16, v55
	v_and_b32_e32 v103, 0xffff0000, v55
	v_lshlrev_b32_e32 v106, 16, v59
	v_and_b32_e32 v107, 0xffff0000, v59
	v_mov_b32_e32 v134, v124
	v_mov_b32_e32 v135, v125
	v_mov_b32_e32 v150, v126
	v_mov_b32_e32 v151, v127
	v_mov_b32_e32 v148, v128
	v_mov_b32_e32 v149, v129
	v_mov_b32_e32 v146, v130
	v_mov_b32_e32 v147, v131
	v_mov_b32_e32 v144, v132
	v_mov_b32_e32 v145, v133
	v_mov_b32_e32 v142, v136
	v_mov_b32_e32 v143, v137
	v_mov_b32_e32 v152, v138
	v_mov_b32_e32 v153, v139
	v_mov_b32_e32 v154, v140
	v_mov_b32_e32 v155, v141
	v_lshlrev_b64 v[0:1], 10, v[64:65]
	global_load_dwordx4 v[4:7], v[88:89], off
	global_load_dwordx4 v[8:11], v[90:91], off
	v_pk_fma_f32 v[16:17], v[96:97], s[26:27], v[134:135] op_sel_hi:[1,0,1]
	v_pk_fma_f32 v[18:19], v[98:99], s[26:27], v[150:151] op_sel_hi:[1,0,1]
	v_add_f32_e32 v2, 0, v16
	v_add_f32_e32 v2, v17, v2
	v_add_f32_e32 v2, v18, v2
	v_add_f32_e32 v2, v19, v2
	v_pk_fma_f32 v[20:21], v[100:101], s[26:27], v[148:149] op_sel_hi:[1,0,1]
	v_pk_fma_f32 v[22:23], v[102:103], s[26:27], v[146:147] op_sel_hi:[1,0,1]
	v_add_f32_e32 v2, v20, v2
	v_add_f32_e32 v2, v21, v2
	v_add_f32_e32 v2, v22, v2
	v_add_f32_e32 v2, v23, v2
	v_pk_fma_f32 v[24:25], v[92:93], s[26:27], v[144:145] op_sel_hi:[1,0,1]
	v_pk_fma_f32 v[26:27], v[94:95], s[26:27], v[142:143] op_sel_hi:[1,0,1]
	v_add_f32_e32 v2, v24, v2
	v_add_f32_e32 v2, v25, v2
	v_add_f32_e32 v2, v26, v2
	v_pk_fma_f32 v[12:13], v[104:105], s[26:27], v[152:153] op_sel_hi:[1,0,1]
	v_add_f32_e32 v2, v27, v2
	v_add_f32_e32 v2, v12, v2
	v_pk_fma_f32 v[14:15], v[106:107], s[26:27], v[154:155] op_sel_hi:[1,0,1]
	v_add_f32_e32 v2, v13, v2
	v_add_f32_e32 v2, v14, v2
	v_add_f32_e32 v2, v15, v2
	v_mov_b32_e32 v28, 0
	v_lshl_add_u64 v[0:1], v[0:1], 2, v[86:87]
	v_add_f32_dpp v2, v2, v2 quad_perm:[1,0,3,2] row_mask:0xf bank_mask:0xf bound_ctrl:1
	s_nop 0
	s_nop 0
	v_add_f32_dpp v2, v2, v2 quad_perm:[2,3,0,1] row_mask:0xf bank_mask:0xf bound_ctrl:1
	s_nop 0
	s_nop 0
	v_add_f32_dpp v2, v2, v2 row_half_mirror row_mask:0xf bank_mask:0xf bound_ctrl:1
	s_nop 1
	v_add_f32_dpp v2, v2, v2 row_mirror row_mask:0xf bank_mask:0xf bound_ctrl:1
	s_nop 1
	v_mov_b32_dpp v28, v2 row_bcast:15 row_mask:0xa bank_mask:0xf
	v_add_f32_e32 v2, v2, v28
	v_mov_b32_e32 v28, 0
	s_nop 1
	v_mov_b32_dpp v28, v2 row_bcast:31 row_mask:0xc bank_mask:0xf
	v_add_f32_e32 v2, v2, v28
	s_nop 0
	v_readlane_b32 s34, v2, 63
	s_nop 1
	v_mul_f32_e32 v2, s34, v180
	v_pk_add_f32 v[16:17], v[16:17], v[2:3] op_sel_hi:[1,0] neg_lo:[0,1] neg_hi:[0,1]
	v_pk_add_f32 v[18:19], v[18:19], v[2:3] op_sel_hi:[1,0] neg_lo:[0,1] neg_hi:[0,1]
	v_pk_mul_f32 v[28:29], v[16:17], v[16:17]
	v_pk_mul_f32 v[30:31], v[18:19], v[18:19]
	v_pk_add_f32 v[20:21], v[20:21], v[2:3] op_sel_hi:[1,0] neg_lo:[0,1] neg_hi:[0,1]
	v_pk_add_f32 v[22:23], v[22:23], v[2:3] op_sel_hi:[1,0] neg_lo:[0,1] neg_hi:[0,1]
	v_pk_add_f32 v[24:25], v[24:25], v[2:3] op_sel_hi:[1,0] neg_lo:[0,1] neg_hi:[0,1]
	v_pk_add_f32 v[26:27], v[26:27], v[2:3] op_sel_hi:[1,0] neg_lo:[0,1] neg_hi:[0,1]
	v_pk_add_f32 v[12:13], v[12:13], v[2:3] op_sel_hi:[1,0] neg_lo:[0,1] neg_hi:[0,1]
	v_pk_add_f32 v[14:15], v[14:15], v[2:3] op_sel_hi:[1,0] neg_lo:[0,1] neg_hi:[0,1]
	v_add_f32_e32 v2, v28, v29
	v_add_f32_e32 v2, v30, v2
	v_pk_mul_f32 v[32:33], v[20:21], v[20:21]
	v_add_f32_e32 v2, v31, v2
	v_add_f32_e32 v2, v32, v2
	v_pk_mul_f32 v[34:35], v[22:23], v[22:23]
	v_add_f32_e32 v2, v33, v2
	v_add_f32_e32 v2, v34, v2
	v_pk_mul_f32 v[36:37], v[24:25], v[24:25]
	v_add_f32_e32 v2, v35, v2
	v_add_f32_e32 v2, v36, v2
	v_pk_mul_f32 v[38:39], v[26:27], v[26:27]
	v_add_f32_e32 v2, v37, v2
	v_add_f32_e32 v2, v38, v2
	v_pk_mul_f32 v[40:41], v[12:13], v[12:13]
	v_add_f32_e32 v2, v39, v2
	v_add_f32_e32 v2, v40, v2
	v_pk_mul_f32 v[42:43], v[14:15], v[14:15]
	v_add_f32_e32 v2, v41, v2
	v_add_f32_e32 v2, v42, v2
	v_add_f32_e32 v2, v43, v2
	v_mov_b32_e32 v28, 0
	s_nop 0
	v_add_f32_dpp v2, v2, v2 quad_perm:[1,0,3,2] row_mask:0xf bank_mask:0xf bound_ctrl:1
	s_nop 1
	v_add_f32_dpp v2, v2, v2 quad_perm:[2,3,0,1] row_mask:0xf bank_mask:0xf bound_ctrl:1
	s_nop 1
	v_add_f32_dpp v2, v2, v2 row_half_mirror row_mask:0xf bank_mask:0xf bound_ctrl:1
	s_nop 1
	v_add_f32_dpp v2, v2, v2 row_mirror row_mask:0xf bank_mask:0xf bound_ctrl:1
	s_nop 1
	v_mov_b32_dpp v28, v2 row_bcast:15 row_mask:0xa bank_mask:0xf
	v_add_f32_e32 v2, v2, v28
	v_mov_b32_e32 v28, 0
	s_nop 1
	v_mov_b32_dpp v28, v2 row_bcast:31 row_mask:0xc bank_mask:0xf
	v_add_f32_e32 v2, v2, v28
	s_nop 0
	v_readlane_b32 s34, v2, 63
	s_nop 1
	v_fma_f32 v2, s34, v180, v177
	v_mul_f32_e32 v28, 0x4b800000, v2
	v_cmp_gt_f32_e32 vcc, s49, v2
	s_nop 1
	v_cndmask_b32_e32 v2, v2, v28, vcc
	v_rsq_f32_e32 v2, v2
	s_nop 0
	v_mul_f32_e32 v28, 0x45800000, v2
	v_cndmask_b32_e32 v2, v2, v28, vcc
	v_pk_mul_f32 v[16:17], v[16:17], v[2:3] op_sel_hi:[1,0]
	v_pk_mul_f32 v[18:19], v[18:19], v[2:3] op_sel_hi:[1,0]
	s_waitcnt vmcnt(0)
	v_pk_fma_f32 v[4:5], v[4:5], v[16:17], v[8:9]
	v_pk_fma_f32 v[6:7], v[6:7], v[18:19], v[10:11]
	global_store_dwordx4 v[0:1], v[4:7], off
	global_load_dwordx4 v[4:7], v[88:89], off offset:16
	s_nop 0
	global_load_dwordx4 v[8:11], v[90:91], off offset:16
	v_pk_mul_f32 v[16:17], v[22:23], v[2:3] op_sel_hi:[1,0]
	v_pk_mul_f32 v[18:19], v[20:21], v[2:3] op_sel_hi:[1,0]
	v_pk_mul_f32 v[14:15], v[14:15], v[2:3] op_sel_hi:[1,0]
	v_pk_mul_f32 v[12:13], v[12:13], v[2:3] op_sel_hi:[1,0]
	s_waitcnt vmcnt(0)
	v_pk_fma_f32 v[4:5], v[4:5], v[18:19], v[8:9]
	v_pk_fma_f32 v[6:7], v[6:7], v[16:17], v[10:11]
	global_store_dwordx4 v[0:1], v[4:7], off offset:16
	global_load_dwordx4 v[4:7], v[88:89], off offset:32
	s_nop 0
	global_load_dwordx4 v[8:11], v[90:91], off offset:32
	v_pk_mul_f32 v[16:17], v[26:27], v[2:3] op_sel_hi:[1,0]
	v_pk_mul_f32 v[18:19], v[24:25], v[2:3] op_sel_hi:[1,0]
	s_waitcnt vmcnt(0)
	v_pk_fma_f32 v[6:7], v[6:7], v[16:17], v[10:11]
	v_pk_fma_f32 v[4:5], v[4:5], v[18:19], v[8:9]
	global_store_dwordx4 v[0:1], v[4:7], off offset:32
	global_load_dwordx4 v[4:7], v[88:89], off offset:48
	s_nop 0
	global_load_dwordx4 v[8:11], v[90:91], off offset:48
	s_waitcnt vmcnt(0)
	v_pk_fma_f32 v[4:5], v[12:13], v[4:5], v[8:9]
	v_pk_fma_f32 v[6:7], v[14:15], v[6:7], v[10:11]
	global_store_dwordx4 v[0:1], v[4:7], off offset:48
	s_lshl_b32 s10, s12, 2
	s_add_i32 s10, s10, 2
	v_add_u32_e32 v64, s10, v79
	v_ashrrev_i32_e32 v65, 31, v64
	v_lshl_add_u64 v[64:65], s[28:29], 0, v[64:65]
	v_lshlrev_b64 v[0:1], 11, v[64:65]
	v_lshl_add_u64 v[0:1], v[80:81], 0, v[0:1]
	v_mov_b32_e32 v52, v216
	v_mov_b32_e32 v53, v217
	v_mov_b32_e32 v54, v218
	v_mov_b32_e32 v55, v219
	v_mov_b32_e32 v56, v220
	v_mov_b32_e32 v57, v221
	v_mov_b32_e32 v58, v222
	v_mov_b32_e32 v59, v223
	v_lshlrev_b32_e32 v96, 16, v52
	v_and_b32_e32 v97, 0xffff0000, v52
	v_lshlrev_b32_e32 v92, 16, v56
	v_and_b32_e32 v93, 0xffff0000, v56
	v_lshlrev_b32_e32 v98, 16, v53
	v_and_b32_e32 v99, 0xffff0000, v53
	v_lshlrev_b32_e32 v94, 16, v57
	v_and_b32_e32 v95, 0xffff0000, v57
	v_lshlrev_b32_e32 v100, 16, v54
	v_and_b32_e32 v101, 0xffff0000, v54
	v_lshlrev_b32_e32 v104, 16, v58
	v_and_b32_e32 v105, 0xffff0000, v58
	v_lshlrev_b32_e32 v102, 16, v55
	v_and_b32_e32 v103, 0xffff0000, v55
	v_lshlrev_b32_e32 v106, 16, v59
	v_and_b32_e32 v107, 0xffff0000, v59
	v_mov_b32_e32 v134, v188
	v_mov_b32_e32 v135, v189
	v_mov_b32_e32 v150, v190
	v_mov_b32_e32 v151, v191
	v_mov_b32_e32 v148, v192
	v_mov_b32_e32 v149, v193
	v_mov_b32_e32 v146, v194
	v_mov_b32_e32 v147, v195
	v_mov_b32_e32 v144, v196
	v_mov_b32_e32 v145, v197
	v_mov_b32_e32 v142, v198
	v_mov_b32_e32 v143, v199
	v_mov_b32_e32 v152, v200
	v_mov_b32_e32 v153, v201
	v_mov_b32_e32 v154, v202
	v_mov_b32_e32 v155, v203
	v_lshlrev_b64 v[0:1], 10, v[64:65]
	global_load_dwordx4 v[4:7], v[88:89], off
	global_load_dwordx4 v[8:11], v[90:91], off
	v_pk_fma_f32 v[16:17], v[96:97], s[26:27], v[134:135] op_sel_hi:[1,0,1]
	v_pk_fma_f32 v[18:19], v[98:99], s[26:27], v[150:151] op_sel_hi:[1,0,1]
	v_add_f32_e32 v2, 0, v16
	v_add_f32_e32 v2, v17, v2
	v_add_f32_e32 v2, v18, v2
	v_add_f32_e32 v2, v19, v2
	v_pk_fma_f32 v[20:21], v[100:101], s[26:27], v[148:149] op_sel_hi:[1,0,1]
	v_pk_fma_f32 v[22:23], v[102:103], s[26:27], v[146:147] op_sel_hi:[1,0,1]
	v_add_f32_e32 v2, v20, v2
	v_add_f32_e32 v2, v21, v2
	v_add_f32_e32 v2, v22, v2
	v_add_f32_e32 v2, v23, v2
	v_pk_fma_f32 v[24:25], v[92:93], s[26:27], v[144:145] op_sel_hi:[1,0,1]
	v_pk_fma_f32 v[26:27], v[94:95], s[26:27], v[142:143] op_sel_hi:[1,0,1]
	v_add_f32_e32 v2, v24, v2
	v_add_f32_e32 v2, v25, v2
	v_add_f32_e32 v2, v26, v2
	v_pk_fma_f32 v[12:13], v[104:105], s[26:27], v[152:153] op_sel_hi:[1,0,1]
	v_add_f32_e32 v2, v27, v2
	v_add_f32_e32 v2, v12, v2
	v_pk_fma_f32 v[14:15], v[106:107], s[26:27], v[154:155] op_sel_hi:[1,0,1]
	v_add_f32_e32 v2, v13, v2
	v_add_f32_e32 v2, v14, v2
	v_add_f32_e32 v2, v15, v2
	v_mov_b32_e32 v28, 0
	v_lshl_add_u64 v[0:1], v[0:1], 2, v[86:87]
	v_add_f32_dpp v2, v2, v2 quad_perm:[1,0,3,2] row_mask:0xf bank_mask:0xf bound_ctrl:1
	s_nop 0
	s_nop 0
	v_add_f32_dpp v2, v2, v2 quad_perm:[2,3,0,1] row_mask:0xf bank_mask:0xf bound_ctrl:1
	s_nop 0
	s_nop 0
	v_add_f32_dpp v2, v2, v2 row_half_mirror row_mask:0xf bank_mask:0xf bound_ctrl:1
	s_nop 1
	v_add_f32_dpp v2, v2, v2 row_mirror row_mask:0xf bank_mask:0xf bound_ctrl:1
	s_nop 1
	v_mov_b32_dpp v28, v2 row_bcast:15 row_mask:0xa bank_mask:0xf
	v_add_f32_e32 v2, v2, v28
	v_mov_b32_e32 v28, 0
	s_nop 1
	v_mov_b32_dpp v28, v2 row_bcast:31 row_mask:0xc bank_mask:0xf
	v_add_f32_e32 v2, v2, v28
	s_nop 0
	v_readlane_b32 s34, v2, 63
	s_nop 1
	v_mul_f32_e32 v2, s34, v180
	v_pk_add_f32 v[16:17], v[16:17], v[2:3] op_sel_hi:[1,0] neg_lo:[0,1] neg_hi:[0,1]
	v_pk_add_f32 v[18:19], v[18:19], v[2:3] op_sel_hi:[1,0] neg_lo:[0,1] neg_hi:[0,1]
	v_pk_mul_f32 v[28:29], v[16:17], v[16:17]
	v_pk_mul_f32 v[30:31], v[18:19], v[18:19]
	v_pk_add_f32 v[20:21], v[20:21], v[2:3] op_sel_hi:[1,0] neg_lo:[0,1] neg_hi:[0,1]
	v_pk_add_f32 v[22:23], v[22:23], v[2:3] op_sel_hi:[1,0] neg_lo:[0,1] neg_hi:[0,1]
	v_pk_add_f32 v[24:25], v[24:25], v[2:3] op_sel_hi:[1,0] neg_lo:[0,1] neg_hi:[0,1]
	v_pk_add_f32 v[26:27], v[26:27], v[2:3] op_sel_hi:[1,0] neg_lo:[0,1] neg_hi:[0,1]
	v_pk_add_f32 v[12:13], v[12:13], v[2:3] op_sel_hi:[1,0] neg_lo:[0,1] neg_hi:[0,1]
	v_pk_add_f32 v[14:15], v[14:15], v[2:3] op_sel_hi:[1,0] neg_lo:[0,1] neg_hi:[0,1]
	v_add_f32_e32 v2, v28, v29
	v_add_f32_e32 v2, v30, v2
	v_pk_mul_f32 v[32:33], v[20:21], v[20:21]
	v_add_f32_e32 v2, v31, v2
	v_add_f32_e32 v2, v32, v2
	v_pk_mul_f32 v[34:35], v[22:23], v[22:23]
	v_add_f32_e32 v2, v33, v2
	v_add_f32_e32 v2, v34, v2
	v_pk_mul_f32 v[36:37], v[24:25], v[24:25]
	v_add_f32_e32 v2, v35, v2
	v_add_f32_e32 v2, v36, v2
	v_pk_mul_f32 v[38:39], v[26:27], v[26:27]
	v_add_f32_e32 v2, v37, v2
	v_add_f32_e32 v2, v38, v2
	v_pk_mul_f32 v[40:41], v[12:13], v[12:13]
	v_add_f32_e32 v2, v39, v2
	v_add_f32_e32 v2, v40, v2
	v_pk_mul_f32 v[42:43], v[14:15], v[14:15]
	v_add_f32_e32 v2, v41, v2
	v_add_f32_e32 v2, v42, v2
	v_add_f32_e32 v2, v43, v2
	v_mov_b32_e32 v28, 0
	s_nop 0
	v_add_f32_dpp v2, v2, v2 quad_perm:[1,0,3,2] row_mask:0xf bank_mask:0xf bound_ctrl:1
	s_nop 1
	v_add_f32_dpp v2, v2, v2 quad_perm:[2,3,0,1] row_mask:0xf bank_mask:0xf bound_ctrl:1
	s_nop 1
	v_add_f32_dpp v2, v2, v2 row_half_mirror row_mask:0xf bank_mask:0xf bound_ctrl:1
	s_nop 1
	v_add_f32_dpp v2, v2, v2 row_mirror row_mask:0xf bank_mask:0xf bound_ctrl:1
	s_nop 1
	v_mov_b32_dpp v28, v2 row_bcast:15 row_mask:0xa bank_mask:0xf
	v_add_f32_e32 v2, v2, v28
	v_mov_b32_e32 v28, 0
	s_nop 1
	v_mov_b32_dpp v28, v2 row_bcast:31 row_mask:0xc bank_mask:0xf
	v_add_f32_e32 v2, v2, v28
	s_nop 0
	v_readlane_b32 s34, v2, 63
	s_nop 1
	v_fma_f32 v2, s34, v180, v177
	v_mul_f32_e32 v28, 0x4b800000, v2
	v_cmp_gt_f32_e32 vcc, s49, v2
	s_nop 1
	v_cndmask_b32_e32 v2, v2, v28, vcc
	v_rsq_f32_e32 v2, v2
	s_nop 0
	v_mul_f32_e32 v28, 0x45800000, v2
	v_cndmask_b32_e32 v2, v2, v28, vcc
	v_pk_mul_f32 v[16:17], v[16:17], v[2:3] op_sel_hi:[1,0]
	v_pk_mul_f32 v[18:19], v[18:19], v[2:3] op_sel_hi:[1,0]
	s_waitcnt vmcnt(0)
	v_pk_fma_f32 v[4:5], v[4:5], v[16:17], v[8:9]
	v_pk_fma_f32 v[6:7], v[6:7], v[18:19], v[10:11]
	global_store_dwordx4 v[0:1], v[4:7], off
	global_load_dwordx4 v[4:7], v[88:89], off offset:16
	s_nop 0
	global_load_dwordx4 v[8:11], v[90:91], off offset:16
	v_pk_mul_f32 v[16:17], v[22:23], v[2:3] op_sel_hi:[1,0]
	v_pk_mul_f32 v[18:19], v[20:21], v[2:3] op_sel_hi:[1,0]
	v_pk_mul_f32 v[14:15], v[14:15], v[2:3] op_sel_hi:[1,0]
	v_pk_mul_f32 v[12:13], v[12:13], v[2:3] op_sel_hi:[1,0]
	s_waitcnt vmcnt(0)
	v_pk_fma_f32 v[4:5], v[4:5], v[18:19], v[8:9]
	v_pk_fma_f32 v[6:7], v[6:7], v[16:17], v[10:11]
	global_store_dwordx4 v[0:1], v[4:7], off offset:16
	global_load_dwordx4 v[4:7], v[88:89], off offset:32
	s_nop 0
	global_load_dwordx4 v[8:11], v[90:91], off offset:32
	v_pk_mul_f32 v[16:17], v[26:27], v[2:3] op_sel_hi:[1,0]
	v_pk_mul_f32 v[18:19], v[24:25], v[2:3] op_sel_hi:[1,0]
	s_waitcnt vmcnt(0)
	v_pk_fma_f32 v[6:7], v[6:7], v[16:17], v[10:11]
	v_pk_fma_f32 v[4:5], v[4:5], v[18:19], v[8:9]
	global_store_dwordx4 v[0:1], v[4:7], off offset:32
	global_load_dwordx4 v[4:7], v[88:89], off offset:48
	s_nop 0
	global_load_dwordx4 v[8:11], v[90:91], off offset:48
	s_waitcnt vmcnt(0)
	v_pk_fma_f32 v[4:5], v[12:13], v[4:5], v[8:9]
	v_pk_fma_f32 v[6:7], v[14:15], v[6:7], v[10:11]
	global_store_dwordx4 v[0:1], v[4:7], off offset:48
	s_lshl_b32 s10, s12, 2
	s_add_i32 s10, s10, 3
	v_add_u32_e32 v64, s10, v79
	v_ashrrev_i32_e32 v65, 31, v64
	v_lshl_add_u64 v[64:65], s[28:29], 0, v[64:65]
	v_lshlrev_b64 v[0:1], 11, v[64:65]
	v_lshl_add_u64 v[0:1], v[80:81], 0, v[0:1]
	v_mov_b32_e32 v52, v224
	v_mov_b32_e32 v53, v225
	v_mov_b32_e32 v54, v226
	v_mov_b32_e32 v55, v227
	v_mov_b32_e32 v56, v228
	v_mov_b32_e32 v57, v229
	v_mov_b32_e32 v58, v230
	v_mov_b32_e32 v59, v231
	v_lshlrev_b32_e32 v96, 16, v52
	v_and_b32_e32 v97, 0xffff0000, v52
	v_lshlrev_b32_e32 v92, 16, v56
	v_and_b32_e32 v93, 0xffff0000, v56
	v_lshlrev_b32_e32 v98, 16, v53
	v_and_b32_e32 v99, 0xffff0000, v53
	v_lshlrev_b32_e32 v94, 16, v57
	v_and_b32_e32 v95, 0xffff0000, v57
	v_lshlrev_b32_e32 v100, 16, v54
	v_and_b32_e32 v101, 0xffff0000, v54
	v_lshlrev_b32_e32 v104, 16, v58
	v_and_b32_e32 v105, 0xffff0000, v58
	v_lshlrev_b32_e32 v102, 16, v55
	v_and_b32_e32 v103, 0xffff0000, v55
	v_lshlrev_b32_e32 v106, 16, v59
	v_and_b32_e32 v107, 0xffff0000, v59
	v_mov_b32_e32 v134, v204
	v_mov_b32_e32 v135, v205
	v_mov_b32_e32 v150, v206
	v_mov_b32_e32 v151, v207
	v_mov_b32_e32 v148, v208
	v_mov_b32_e32 v149, v209
	v_mov_b32_e32 v146, v210
	v_mov_b32_e32 v147, v211
	v_mov_b32_e32 v144, v212
	v_mov_b32_e32 v145, v213
	v_mov_b32_e32 v142, v186
	v_mov_b32_e32 v143, v187
	v_mov_b32_e32 v152, v66
	v_mov_b32_e32 v153, v67
	v_mov_b32_e32 v154, v68
	v_mov_b32_e32 v155, v69
	v_lshlrev_b64 v[0:1], 10, v[64:65]
	global_load_dwordx4 v[4:7], v[88:89], off
	global_load_dwordx4 v[8:11], v[90:91], off
	v_pk_fma_f32 v[16:17], v[96:97], s[26:27], v[134:135] op_sel_hi:[1,0,1]
	v_pk_fma_f32 v[18:19], v[98:99], s[26:27], v[150:151] op_sel_hi:[1,0,1]
	v_add_f32_e32 v2, 0, v16
	v_add_f32_e32 v2, v17, v2
	v_add_f32_e32 v2, v18, v2
	v_add_f32_e32 v2, v19, v2
	v_pk_fma_f32 v[20:21], v[100:101], s[26:27], v[148:149] op_sel_hi:[1,0,1]
	v_pk_fma_f32 v[22:23], v[102:103], s[26:27], v[146:147] op_sel_hi:[1,0,1]
	v_add_f32_e32 v2, v20, v2
	v_add_f32_e32 v2, v21, v2
	v_add_f32_e32 v2, v22, v2
	v_add_f32_e32 v2, v23, v2
	v_pk_fma_f32 v[24:25], v[92:93], s[26:27], v[144:145] op_sel_hi:[1,0,1]
	v_pk_fma_f32 v[26:27], v[94:95], s[26:27], v[142:143] op_sel_hi:[1,0,1]
	v_add_f32_e32 v2, v24, v2
	v_add_f32_e32 v2, v25, v2
	v_add_f32_e32 v2, v26, v2
	v_pk_fma_f32 v[12:13], v[104:105], s[26:27], v[152:153] op_sel_hi:[1,0,1]
	v_add_f32_e32 v2, v27, v2
	v_add_f32_e32 v2, v12, v2
	v_pk_fma_f32 v[14:15], v[106:107], s[26:27], v[154:155] op_sel_hi:[1,0,1]
	v_add_f32_e32 v2, v13, v2
	v_add_f32_e32 v2, v14, v2
	v_add_f32_e32 v2, v15, v2
	v_mov_b32_e32 v28, 0
	v_lshl_add_u64 v[0:1], v[0:1], 2, v[86:87]
	v_add_f32_dpp v2, v2, v2 quad_perm:[1,0,3,2] row_mask:0xf bank_mask:0xf bound_ctrl:1
	s_nop 0
	s_nop 0
	v_add_f32_dpp v2, v2, v2 quad_perm:[2,3,0,1] row_mask:0xf bank_mask:0xf bound_ctrl:1
	s_nop 0
	s_nop 0
	v_add_f32_dpp v2, v2, v2 row_half_mirror row_mask:0xf bank_mask:0xf bound_ctrl:1
	s_nop 1
	v_add_f32_dpp v2, v2, v2 row_mirror row_mask:0xf bank_mask:0xf bound_ctrl:1
	s_nop 1
	v_mov_b32_dpp v28, v2 row_bcast:15 row_mask:0xa bank_mask:0xf
	v_add_f32_e32 v2, v2, v28
	v_mov_b32_e32 v28, 0
	s_nop 1
	v_mov_b32_dpp v28, v2 row_bcast:31 row_mask:0xc bank_mask:0xf
	v_add_f32_e32 v2, v2, v28
	s_nop 0
	v_readlane_b32 s34, v2, 63
	s_nop 1
	v_mul_f32_e32 v2, s34, v180
	v_pk_add_f32 v[16:17], v[16:17], v[2:3] op_sel_hi:[1,0] neg_lo:[0,1] neg_hi:[0,1]
	v_pk_add_f32 v[18:19], v[18:19], v[2:3] op_sel_hi:[1,0] neg_lo:[0,1] neg_hi:[0,1]
	v_pk_mul_f32 v[28:29], v[16:17], v[16:17]
	v_pk_mul_f32 v[30:31], v[18:19], v[18:19]
	v_pk_add_f32 v[20:21], v[20:21], v[2:3] op_sel_hi:[1,0] neg_lo:[0,1] neg_hi:[0,1]
	v_pk_add_f32 v[22:23], v[22:23], v[2:3] op_sel_hi:[1,0] neg_lo:[0,1] neg_hi:[0,1]
	v_pk_add_f32 v[24:25], v[24:25], v[2:3] op_sel_hi:[1,0] neg_lo:[0,1] neg_hi:[0,1]
	v_pk_add_f32 v[26:27], v[26:27], v[2:3] op_sel_hi:[1,0] neg_lo:[0,1] neg_hi:[0,1]
	v_pk_add_f32 v[12:13], v[12:13], v[2:3] op_sel_hi:[1,0] neg_lo:[0,1] neg_hi:[0,1]
	v_pk_add_f32 v[14:15], v[14:15], v[2:3] op_sel_hi:[1,0] neg_lo:[0,1] neg_hi:[0,1]
	v_add_f32_e32 v2, v28, v29
	v_add_f32_e32 v2, v30, v2
	v_pk_mul_f32 v[32:33], v[20:21], v[20:21]
	v_add_f32_e32 v2, v31, v2
	v_add_f32_e32 v2, v32, v2
	v_pk_mul_f32 v[34:35], v[22:23], v[22:23]
	v_add_f32_e32 v2, v33, v2
	v_add_f32_e32 v2, v34, v2
	v_pk_mul_f32 v[36:37], v[24:25], v[24:25]
	v_add_f32_e32 v2, v35, v2
	v_add_f32_e32 v2, v36, v2
	v_pk_mul_f32 v[38:39], v[26:27], v[26:27]
	v_add_f32_e32 v2, v37, v2
	v_add_f32_e32 v2, v38, v2
	v_pk_mul_f32 v[40:41], v[12:13], v[12:13]
	v_add_f32_e32 v2, v39, v2
	v_add_f32_e32 v2, v40, v2
	v_pk_mul_f32 v[42:43], v[14:15], v[14:15]
	v_add_f32_e32 v2, v41, v2
	v_add_f32_e32 v2, v42, v2
	v_add_f32_e32 v2, v43, v2
	v_mov_b32_e32 v28, 0
	s_nop 0
	v_add_f32_dpp v2, v2, v2 quad_perm:[1,0,3,2] row_mask:0xf bank_mask:0xf bound_ctrl:1
	s_nop 1
	v_add_f32_dpp v2, v2, v2 quad_perm:[2,3,0,1] row_mask:0xf bank_mask:0xf bound_ctrl:1
	s_nop 1
	v_add_f32_dpp v2, v2, v2 row_half_mirror row_mask:0xf bank_mask:0xf bound_ctrl:1
	s_nop 1
	v_add_f32_dpp v2, v2, v2 row_mirror row_mask:0xf bank_mask:0xf bound_ctrl:1
	s_nop 1
	v_mov_b32_dpp v28, v2 row_bcast:15 row_mask:0xa bank_mask:0xf
	v_add_f32_e32 v2, v2, v28
	v_mov_b32_e32 v28, 0
	s_nop 1
	v_mov_b32_dpp v28, v2 row_bcast:31 row_mask:0xc bank_mask:0xf
	v_add_f32_e32 v2, v2, v28
	s_nop 0
	v_readlane_b32 s34, v2, 63
	s_nop 1
	v_fma_f32 v2, s34, v180, v177
	v_mul_f32_e32 v28, 0x4b800000, v2
	v_cmp_gt_f32_e32 vcc, s49, v2
	s_nop 1
	v_cndmask_b32_e32 v2, v2, v28, vcc
	v_rsq_f32_e32 v2, v2
	s_nop 0
	v_mul_f32_e32 v28, 0x45800000, v2
	v_cndmask_b32_e32 v2, v2, v28, vcc
	v_pk_mul_f32 v[16:17], v[16:17], v[2:3] op_sel_hi:[1,0]
	v_pk_mul_f32 v[18:19], v[18:19], v[2:3] op_sel_hi:[1,0]
	s_waitcnt vmcnt(0)
	v_pk_fma_f32 v[4:5], v[4:5], v[16:17], v[8:9]
	v_pk_fma_f32 v[6:7], v[6:7], v[18:19], v[10:11]
	global_store_dwordx4 v[0:1], v[4:7], off
	global_load_dwordx4 v[4:7], v[88:89], off offset:16
	s_nop 0
	global_load_dwordx4 v[8:11], v[90:91], off offset:16
	v_pk_mul_f32 v[16:17], v[22:23], v[2:3] op_sel_hi:[1,0]
	v_pk_mul_f32 v[18:19], v[20:21], v[2:3] op_sel_hi:[1,0]
	v_pk_mul_f32 v[14:15], v[14:15], v[2:3] op_sel_hi:[1,0]
	v_pk_mul_f32 v[12:13], v[12:13], v[2:3] op_sel_hi:[1,0]
	s_waitcnt vmcnt(0)
	v_pk_fma_f32 v[4:5], v[4:5], v[18:19], v[8:9]
	v_pk_fma_f32 v[6:7], v[6:7], v[16:17], v[10:11]
	global_store_dwordx4 v[0:1], v[4:7], off offset:16
	global_load_dwordx4 v[4:7], v[88:89], off offset:32
	s_nop 0
	global_load_dwordx4 v[8:11], v[90:91], off offset:32
	v_pk_mul_f32 v[16:17], v[26:27], v[2:3] op_sel_hi:[1,0]
	v_pk_mul_f32 v[18:19], v[24:25], v[2:3] op_sel_hi:[1,0]
	s_waitcnt vmcnt(0)
	v_pk_fma_f32 v[6:7], v[6:7], v[16:17], v[10:11]
	v_pk_fma_f32 v[4:5], v[4:5], v[18:19], v[8:9]
	global_store_dwordx4 v[0:1], v[4:7], off offset:32
	global_load_dwordx4 v[4:7], v[88:89], off offset:48
	s_nop 0
	global_load_dwordx4 v[8:11], v[90:91], off offset:48
	s_waitcnt vmcnt(0)
	v_pk_fma_f32 v[4:5], v[12:13], v[4:5], v[8:9]
	v_pk_fma_f32 v[6:7], v[14:15], v[6:7], v[10:11]
	global_store_dwordx4 v[0:1], v[4:7], off offset:48
	s_add_i32 s12, s12, 1
	s_cmp_lt_u32 s12, 2
	s_cbranch_scc1 .Lex_half
	v_mov_b32_e32 v3, 0
	s_branch .LBB0_685
